# GLU epilogue loads batched; in-proj plain/q/silu epilogues as mode-specialised straight-line code
# speedup vs baseline: 1.0286x; 1.0060x over previous
; __device__ __forceinline__ float sigmoidf_(float x) { return __builtin_amdgcn_rcpf(1.0f + __builtin_amdgcn_exp2f(-1.4426950408889634f * x)); }
; __device__ __forceinline__ void unpack8(const u32x4 w, float (&f)[8]) { f[0] = bflo(w.x); f[1] = bfhi(w.x); f[2] = bflo(w.y); f[3] = bfhi(w.y); f[4] = bflo(w.z); f[5] = bfhi(w.z); f[6] = bflo(w.w); f[7] = bfhi(w.w); }
; __device__ __forceinline__ u32x4 pack8(const float (&f)[8]) { u32x4 w; w.x = cvt_pk_bf16(f[0], f[1]); w.y = cvt_pk_bf16(f[2], f[3]); w.z = cvt_pk_bf16(f[4], f[5]); w.w = cvt_pk_bf16(f[6], f[7]); return w; }
;     __device__ __forceinline__ void operator()(const Acc& acc, const Unit& u, int wr, int wc, int fr, int fq) const {
;         const int row0 = u.pm * 256 + wr * 64 + fr, col = u.pn * 128 + wc * 32 + 8 * fq;
; #pragma unroll
;         for (int ai = 0; ai < 2; ++ai)
; #pragma unroll
;             for (int m = 0; m < 4; ++m) { const int row = row0 + ai * 128 + m * 16;
;                 float z[8]; unpack8(*(const u32x4*)(proj + (size_t)row * NIN + 5632 + col), z);
;                 float v[8];
; #pragma unroll
;                 for (int e = 0; e < 4; ++e) { v[e] = acc[ai][0][m][0][e] * sigmoidf_(acc[ai][1][m][0][e]) * z[e]; v[4 + e] = acc[ai][0][m][1][e] * sigmoidf_(acc[ai][1][m][1][e]) * z[4 + e]; }
;                 *(u32x4*)(U + (size_t)row * DM + 1536 + col) = pack8(v); }
;     }
.LBB0_310:
	v_lshl_or_b32 v138, s45, 7, v146
	v_lshl_add_u32 v140, s22, 8, v144
	v_ashrrev_i32_e32 v139, 31, v138
	v_mov_b64_e32 v[142:143], s[6:7]
	v_mad_i64_i32 v[148:149], s[24:25], v140, s68, v[142:143]
	v_lshlrev_b64 v[138:139], 1, v[138:139]
	v_lshl_add_u64 v[148:149], v[148:149], 0, v[138:139]
	v_add_co_u32_e32 v148, vcc, 0x2000, v148
	v_mul_f32_e32 v124, 0xbfb8aa3b, v124
	s_nop 0
	v_addc_co_u32_e32 v149, vcc, 0, v149, vcc
	s_mov_b64 s[24:25], 0x70000
	s_nop 0
	v_lshl_add_u64 v[214:215], v[148:149], 0, s[24:25]
	global_load_dwordx4 v[166:169], v[214:215], off offset:3072
	s_mov_b64 s[24:25], 0xe0000
	s_nop 0
	v_lshl_add_u64 v[214:215], v[148:149], 0, s[24:25]
	global_load_dwordx4 v[170:173], v[214:215], off offset:3072
	s_mov_b64 s[24:25], 0x150000
	s_nop 0
	v_lshl_add_u64 v[214:215], v[148:149], 0, s[24:25]
	global_load_dwordx4 v[174:177], v[214:215], off offset:3072
	s_mov_b64 s[24:25], 0x380000
	s_nop 0
	v_lshl_add_u64 v[214:215], v[148:149], 0, s[24:25]
	global_load_dwordx4 v[178:181], v[214:215], off offset:3072
	s_mov_b64 s[24:25], 0x3f0000
	s_nop 0
	v_lshl_add_u64 v[214:215], v[148:149], 0, s[24:25]
	global_load_dwordx4 v[182:185], v[214:215], off offset:3072
	s_mov_b64 s[24:25], 0x460000
	s_nop 0
	v_lshl_add_u64 v[214:215], v[148:149], 0, s[24:25]
	global_load_dwordx4 v[186:189], v[214:215], off offset:3072
	s_mov_b64 s[24:25], 0x4d0000
	s_nop 0
	v_lshl_add_u64 v[214:215], v[148:149], 0, s[24:25]
	global_load_dwordx4 v[210:213], v[214:215], off offset:3072
	global_load_dwordx4 v[148:151], v[148:149], off offset:3072
	v_mul_f32_e32 v116, 0xbfb8aa3b, v116
	v_mul_f32_e32 v125, 0xbfb8aa3b, v125
	v_mul_f32_e32 v117, 0xbfb8aa3b, v117
	v_exp_f32_e32 v124, v124
	v_exp_f32_e32 v116, v116
	v_exp_f32_e32 v125, v125
	v_exp_f32_e32 v117, v117
	v_add_f32_e32 v124, 1.0, v124
	v_add_f32_e32 v116, 1.0, v116
	v_add_f32_e32 v125, 1.0, v125
	v_add_f32_e32 v117, 1.0, v117
	v_rcp_f32_e32 v124, v124
	v_rcp_f32_e32 v116, v116
	v_rcp_f32_e32 v125, v125
	v_rcp_f32_e32 v117, v117
	v_ashrrev_i32_e32 v141, 31, v140
	v_mul_f32_e32 v108, 0xbfb8aa3b, v108
	v_pk_mul_f32 v[120:121], v[124:125], v[120:121]
	v_pk_mul_f32 v[112:113], v[116:117], v[112:113]
	v_mul_f32_e32 v100, 0xbfb8aa3b, v100
	v_mul_f32_e32 v109, 0xbfb8aa3b, v109
	v_mul_f32_e32 v101, 0xbfb8aa3b, v101
	v_exp_f32_e32 v108, v108
	v_exp_f32_e32 v100, v100
	v_exp_f32_e32 v109, v109
	v_exp_f32_e32 v101, v101
	v_add_f32_e32 v108, 1.0, v108
	v_add_f32_e32 v100, 1.0, v100
	v_add_f32_e32 v109, 1.0, v109
	v_add_f32_e32 v101, 1.0, v101
	v_rcp_f32_e32 v108, v108
	v_rcp_f32_e32 v100, v100
	v_rcp_f32_e32 v109, v109
	v_rcp_f32_e32 v101, v101
	v_mul_f32_e32 v92, 0xbfb8aa3b, v92
	v_mul_f32_e32 v84, 0xbfb8aa3b, v84
	v_pk_mul_f32 v[104:105], v[108:109], v[104:105]
	v_pk_mul_f32 v[96:97], v[100:101], v[96:97]
	v_mul_f32_e32 v93, 0xbfb8aa3b, v93
	v_mul_f32_e32 v85, 0xbfb8aa3b, v85
	v_exp_f32_e32 v92, v92
	v_exp_f32_e32 v84, v84
	v_exp_f32_e32 v93, v93
	v_exp_f32_e32 v85, v85
	v_add_f32_e32 v92, 1.0, v92
	v_add_f32_e32 v84, 1.0, v84
	v_add_f32_e32 v93, 1.0, v93
	v_add_f32_e32 v85, 1.0, v85
	v_rcp_f32_e32 v92, v92
	v_rcp_f32_e32 v84, v84
	v_rcp_f32_e32 v93, v93
	v_rcp_f32_e32 v85, v85
	v_mul_f32_e32 v76, 0xbfb8aa3b, v76
	v_mul_f32_e32 v68, 0xbfb8aa3b, v68
	v_pk_mul_f32 v[88:89], v[92:93], v[88:89]
	v_pk_mul_f32 v[80:81], v[84:85], v[80:81]
	v_mul_f32_e32 v77, 0xbfb8aa3b, v77
	v_mul_f32_e32 v69, 0xbfb8aa3b, v69
	v_exp_f32_e32 v76, v76
	v_exp_f32_e32 v68, v68
	v_exp_f32_e32 v77, v77
	v_exp_f32_e32 v69, v69
	v_add_f32_e32 v76, 1.0, v76
	v_add_f32_e32 v68, 1.0, v68
	v_add_f32_e32 v77, 1.0, v77
	v_add_f32_e32 v69, 1.0, v69
	v_rcp_f32_e32 v76, v76
	v_rcp_f32_e32 v68, v68
	v_rcp_f32_e32 v77, v77
	v_rcp_f32_e32 v69, v69
	v_mul_f32_e32 v60, 0xbfb8aa3b, v60
	v_mul_f32_e32 v52, 0xbfb8aa3b, v52
	v_pk_mul_f32 v[72:73], v[76:77], v[72:73]
	v_pk_mul_f32 v[64:65], v[68:69], v[64:65]
	v_mul_f32_e32 v61, 0xbfb8aa3b, v61
	v_mul_f32_e32 v53, 0xbfb8aa3b, v53
	v_exp_f32_e32 v60, v60
	v_exp_f32_e32 v52, v52
	v_exp_f32_e32 v61, v61
	s_waitcnt vmcnt(0)
	v_lshlrev_b32_e32 v124, 16, v150
	v_and_b32_e32 v125, 0xffff0000, v150
	v_pk_mul_f32 v[116:117], v[112:113], v[124:125]
	v_mul_f32_e32 v113, 0xbfb8aa3b, v118
	v_exp_f32_e32 v113, v113
	v_mul_f32_e32 v112, 0xbfb8aa3b, v126
	v_exp_f32_e32 v112, v112
	v_lshlrev_b32_e32 v124, 16, v149
	v_add_f32_e32 v113, 1.0, v113
	v_rcp_f32_e32 v118, v113
	v_mul_f32_e32 v113, 0xbfb8aa3b, v127
	v_exp_f32_e32 v113, v113
	v_add_f32_e32 v112, 1.0, v112
	v_rcp_f32_e32 v112, v112
	v_and_b32_e32 v125, 0xffff0000, v149
	v_add_f32_e32 v113, 1.0, v113
	v_rcp_f32_e32 v113, v113
	v_lshlrev_b32_e32 v152, 16, v148
	v_and_b32_e32 v153, 0xffff0000, v148
	v_pk_mul_f32 v[120:121], v[120:121], v[152:153]
	v_pk_mul_f32 v[112:113], v[112:113], v[122:123]
	v_exp_f32_e32 v53, v53
	v_pk_mul_f32 v[122:123], v[112:113], v[124:125]
	v_mul_f32_e32 v112, 0xbfb8aa3b, v119
	v_exp_f32_e32 v112, v112
	v_and_b32_e32 v113, 0xffff0000, v151
	v_add_f32_e32 v60, 1.0, v60
	v_add_f32_e32 v52, 1.0, v52
	v_add_f32_e32 v112, 1.0, v112
	v_rcp_f32_e32 v119, v112
	v_lshlrev_b32_e32 v112, 16, v151
	v_add_f32_e32 v61, 1.0, v61
	v_add_f32_e32 v53, 1.0, v53
	v_pk_mul_f32 v[114:115], v[118:119], v[114:115]
	v_rcp_f32_e32 v60, v60
	v_pk_mul_f32 v[118:119], v[114:115], v[112:113]
	v_cvt_pk_bf16_f32 v114, v116, v117
	v_lshlrev_b64 v[116:117], 12, v[140:141]
	v_lshl_add_u64 v[116:117], s[8:9], 0, v[116:117]
	v_cvt_pk_bf16_f32 v112, v120, v121
	v_cvt_pk_bf16_f32 v113, v122, v123
	v_cvt_pk_bf16_f32 v115, v118, v119
	v_lshl_add_u64 v[116:117], v[116:117], 0, v[138:139]
	global_store_dwordx4 v[116:117], v[112:115], off offset:3072
	v_rcp_f32_e32 v52, v52
; __device__ __forceinline__ float sigmoidf_(float x) { return __builtin_amdgcn_rcpf(1.0f + __builtin_amdgcn_exp2f(-1.4426950408889634f * x)); }
; __device__ __forceinline__ void unpack8(const u32x4 w, float (&f)[8]) { f[0] = bflo(w.x); f[1] = bfhi(w.x); f[2] = bflo(w.y); f[3] = bfhi(w.y); f[4] = bflo(w.z); f[5] = bfhi(w.z); f[6] = bflo(w.w); f[7] = bfhi(w.w); }
; __device__ __forceinline__ u32x4 pack8(const float (&f)[8]) { u32x4 w; w.x = cvt_pk_bf16(f[0], f[1]); w.y = cvt_pk_bf16(f[2], f[3]); w.z = cvt_pk_bf16(f[4], f[5]); w.w = cvt_pk_bf16(f[6], f[7]); return w; }
;     __device__ __forceinline__ void operator()(const Acc& acc, const Unit& u, int wr, int wc, int fr, int fq) const {
;         const int row0 = u.pm * 256 + wr * 64 + fr, col = u.pn * 128 + wc * 32 + 8 * fq;
; #pragma unroll
;         for (int ai = 0; ai < 2; ++ai)
; #pragma unroll
;             for (int m = 0; m < 4; ++m) { const int row = row0 + ai * 128 + m * 16;
;                 float z[8]; unpack8(*(const u32x4*)(proj + (size_t)row * NIN + 5632 + col), z);
;                 float v[8];
; #pragma unroll
;                 for (int e = 0; e < 4; ++e) { v[e] = acc[ai][0][m][0][e] * sigmoidf_(acc[ai][1][m][0][e]) * z[e]; v[4 + e] = acc[ai][0][m][1][e] * sigmoidf_(acc[ai][1][m][1][e]) * z[4 + e]; }
;                 *(u32x4*)(U + (size_t)row * DM + 1536 + col) = pack8(v); }
;     }
	v_rcp_f32_e32 v61, v61
	v_or_b32_e32 v112, 16, v140
	v_mad_i64_i32 v[114:115], s[24:25], v112, s68, v[142:143]
	v_lshl_add_u64 v[114:115], v[114:115], 0, v[138:139]
	v_add_co_u32_e32 v114, vcc, s91, v114
	v_ashrrev_i32_e32 v113, 31, v112
	s_nop 0
	v_addc_co_u32_e32 v115, vcc, 0, v115, vcc
	v_mov_b64_e32 v[114:115], v[166:167]
	v_mov_b64_e32 v[116:117], v[168:169]
	v_rcp_f32_e32 v53, v53
	v_pk_mul_f32 v[56:57], v[60:61], v[56:57]
	v_mul_f32_e32 v44, 0xbfb8aa3b, v44
	v_mul_f32_e32 v36, 0xbfb8aa3b, v36
	v_pk_mul_f32 v[48:49], v[52:53], v[48:49]
	v_mul_f32_e32 v45, 0xbfb8aa3b, v45
	v_mul_f32_e32 v37, 0xbfb8aa3b, v37
	v_exp_f32_e32 v44, v44
	v_exp_f32_e32 v36, v36
	v_exp_f32_e32 v45, v45
	v_exp_f32_e32 v37, v37
	v_add_f32_e32 v44, 1.0, v44
	v_add_f32_e32 v36, 1.0, v36
	v_add_f32_e32 v45, 1.0, v45
	v_add_f32_e32 v37, 1.0, v37
	v_rcp_f32_e32 v44, v44
	v_rcp_f32_e32 v36, v36
	v_rcp_f32_e32 v45, v45
	v_rcp_f32_e32 v37, v37
	v_mul_f32_e32 v28, 0xbfb8aa3b, v28
	v_mul_f32_e32 v20, 0xbfb8aa3b, v20
	v_pk_mul_f32 v[40:41], v[44:45], v[40:41]
	v_pk_mul_f32 v[32:33], v[36:37], v[32:33]
	v_mul_f32_e32 v29, 0xbfb8aa3b, v29
	v_mul_f32_e32 v21, 0xbfb8aa3b, v21
	v_exp_f32_e32 v28, v28
	v_exp_f32_e32 v20, v20
	v_exp_f32_e32 v29, v29
	v_exp_f32_e32 v21, v21
	v_add_f32_e32 v28, 1.0, v28
	v_add_f32_e32 v20, 1.0, v20
	v_add_f32_e32 v29, 1.0, v29
	v_add_f32_e32 v21, 1.0, v21
	v_rcp_f32_e32 v28, v28
	v_rcp_f32_e32 v20, v20
	v_rcp_f32_e32 v29, v29
	v_rcp_f32_e32 v21, v21
	v_mul_f32_e32 v12, 0xbfb8aa3b, v12
	v_mul_f32_e32 v4, 0xbfb8aa3b, v4
	v_pk_mul_f32 v[24:25], v[28:29], v[24:25]
	v_pk_mul_f32 v[16:17], v[20:21], v[16:17]
	v_mul_f32_e32 v13, 0xbfb8aa3b, v13
	v_mul_f32_e32 v5, 0xbfb8aa3b, v5
	v_exp_f32_e32 v12, v12
	v_exp_f32_e32 v4, v4
	v_exp_f32_e32 v13, v13
	v_exp_f32_e32 v5, v5
	v_add_f32_e32 v12, 1.0, v12
	v_add_f32_e32 v4, 1.0, v4
	v_add_f32_e32 v13, 1.0, v13
	v_add_f32_e32 v5, 1.0, v5
	v_rcp_f32_e32 v12, v12
	v_rcp_f32_e32 v4, v4
	v_rcp_f32_e32 v13, v13
	v_rcp_f32_e32 v5, v5
	s_mov_b32 s22, s14
	s_mov_b32 s45, s12
	v_pk_mul_f32 v[8:9], v[12:13], v[8:9]
	v_pk_mul_f32 v[0:1], v[4:5], v[0:1]
	s_mov_b64 s[38:39], s[18:19]
	s_nop 0
	v_lshlrev_b32_e32 v108, 16, v116
	v_and_b32_e32 v109, 0xffff0000, v116
	v_pk_mul_f32 v[100:101], v[96:97], v[108:109]
	v_mul_f32_e32 v97, 0xbfb8aa3b, v102
	v_exp_f32_e32 v97, v97
	v_mul_f32_e32 v96, 0xbfb8aa3b, v110
	v_exp_f32_e32 v96, v96
	v_lshlrev_b32_e32 v108, 16, v115
	v_add_f32_e32 v97, 1.0, v97
	v_rcp_f32_e32 v102, v97
	v_mul_f32_e32 v97, 0xbfb8aa3b, v111
	v_exp_f32_e32 v97, v97
	v_add_f32_e32 v96, 1.0, v96
	v_rcp_f32_e32 v96, v96
	v_and_b32_e32 v109, 0xffff0000, v115
	v_add_f32_e32 v97, 1.0, v97
	v_rcp_f32_e32 v97, v97
	v_lshlrev_b32_e32 v118, 16, v114
	v_and_b32_e32 v119, 0xffff0000, v114
	v_pk_mul_f32 v[104:105], v[104:105], v[118:119]
	v_pk_mul_f32 v[96:97], v[96:97], v[106:107]
	s_nop 0
	v_pk_mul_f32 v[106:107], v[96:97], v[108:109]
	v_mul_f32_e32 v96, 0xbfb8aa3b, v103
	v_exp_f32_e32 v96, v96
	v_and_b32_e32 v97, 0xffff0000, v117
	v_add_f32_e32 v96, 1.0, v96
	v_rcp_f32_e32 v103, v96
	v_lshlrev_b32_e32 v96, 16, v117
	v_pk_mul_f32 v[98:99], v[102:103], v[98:99]
	s_nop 0
	v_pk_mul_f32 v[102:103], v[98:99], v[96:97]
	v_cvt_pk_bf16_f32 v98, v100, v101
	v_lshlrev_b64 v[100:101], 12, v[112:113]
	v_lshl_add_u64 v[100:101], s[8:9], 0, v[100:101]
	v_cvt_pk_bf16_f32 v96, v104, v105
	v_cvt_pk_bf16_f32 v97, v106, v107
	v_cvt_pk_bf16_f32 v99, v102, v103
	v_lshl_add_u64 v[100:101], v[100:101], 0, v[138:139]
	global_store_dwordx4 v[100:101], v[96:99], off offset:3072
	s_nop 1
	v_or_b32_e32 v96, 32, v140
	v_mad_i64_i32 v[98:99], s[24:25], v96, s68, v[142:143]
	v_lshl_add_u64 v[98:99], v[98:99], 0, v[138:139]
	v_add_co_u32_e32 v98, vcc, s91, v98
	v_ashrrev_i32_e32 v97, 31, v96
	s_nop 0
	v_addc_co_u32_e32 v99, vcc, 0, v99, vcc
	v_mov_b64_e32 v[98:99], v[170:171]
	v_mov_b64_e32 v[100:101], v[172:173]
	s_nop 0
	v_lshlrev_b32_e32 v92, 16, v100
	v_and_b32_e32 v93, 0xffff0000, v100
	v_pk_mul_f32 v[84:85], v[80:81], v[92:93]
	v_mul_f32_e32 v81, 0xbfb8aa3b, v86
	v_exp_f32_e32 v81, v81
	v_mul_f32_e32 v80, 0xbfb8aa3b, v94
	v_exp_f32_e32 v80, v80
	v_lshlrev_b32_e32 v92, 16, v99
	v_add_f32_e32 v81, 1.0, v81
	v_rcp_f32_e32 v86, v81
	v_mul_f32_e32 v81, 0xbfb8aa3b, v95
	v_exp_f32_e32 v81, v81
	v_add_f32_e32 v80, 1.0, v80
	v_rcp_f32_e32 v80, v80
	v_and_b32_e32 v93, 0xffff0000, v99
	v_add_f32_e32 v81, 1.0, v81
	v_rcp_f32_e32 v81, v81
	v_lshlrev_b32_e32 v102, 16, v98
	v_and_b32_e32 v103, 0xffff0000, v98
	v_pk_mul_f32 v[88:89], v[88:89], v[102:103]
	v_pk_mul_f32 v[80:81], v[80:81], v[90:91]
	s_nop 0
	v_pk_mul_f32 v[90:91], v[80:81], v[92:93]
	v_mul_f32_e32 v80, 0xbfb8aa3b, v87
	v_exp_f32_e32 v80, v80
	v_and_b32_e32 v81, 0xffff0000, v101
	v_add_f32_e32 v80, 1.0, v80
	v_rcp_f32_e32 v87, v80
	v_lshlrev_b32_e32 v80, 16, v101
	v_pk_mul_f32 v[82:83], v[86:87], v[82:83]
	s_nop 0
	v_pk_mul_f32 v[86:87], v[82:83], v[80:81]
	v_cvt_pk_bf16_f32 v82, v84, v85
	v_lshlrev_b64 v[84:85], 12, v[96:97]
	v_lshl_add_u64 v[84:85], s[8:9], 0, v[84:85]
	v_cvt_pk_bf16_f32 v80, v88, v89
	v_cvt_pk_bf16_f32 v81, v90, v91
	v_cvt_pk_bf16_f32 v83, v86, v87
	v_lshl_add_u64 v[84:85], v[84:85], 0, v[138:139]
	global_store_dwordx4 v[84:85], v[80:83], off offset:3072
	s_nop 1
	v_or_b32_e32 v80, 48, v140
	v_mad_i64_i32 v[82:83], s[24:25], v80, s68, v[142:143]
	v_lshl_add_u64 v[82:83], v[82:83], 0, v[138:139]
	v_add_co_u32_e32 v82, vcc, s91, v82
	v_ashrrev_i32_e32 v81, 31, v80
	s_nop 0
	v_addc_co_u32_e32 v83, vcc, 0, v83, vcc
	v_mov_b64_e32 v[82:83], v[174:175]
	v_mov_b64_e32 v[84:85], v[176:177]
	s_nop 0
	v_lshlrev_b32_e32 v76, 16, v84
	v_and_b32_e32 v77, 0xffff0000, v84
	v_pk_mul_f32 v[68:69], v[64:65], v[76:77]
; __device__ __forceinline__ float sigmoidf_(float x) { return __builtin_amdgcn_rcpf(1.0f + __builtin_amdgcn_exp2f(-1.4426950408889634f * x)); }
; __device__ __forceinline__ void unpack8(const u32x4 w, float (&f)[8]) { f[0] = bflo(w.x); f[1] = bfhi(w.x); f[2] = bflo(w.y); f[3] = bfhi(w.y); f[4] = bflo(w.z); f[5] = bfhi(w.z); f[6] = bflo(w.w); f[7] = bfhi(w.w); }
; __device__ __forceinline__ u32x4 pack8(const float (&f)[8]) { u32x4 w; w.x = cvt_pk_bf16(f[0], f[1]); w.y = cvt_pk_bf16(f[2], f[3]); w.z = cvt_pk_bf16(f[4], f[5]); w.w = cvt_pk_bf16(f[6], f[7]); return w; }
;     __device__ __forceinline__ void operator()(const Acc& acc, const Unit& u, int wr, int wc, int fr, int fq) const {
;         const int row0 = u.pm * 256 + wr * 64 + fr, col = u.pn * 128 + wc * 32 + 8 * fq;
; #pragma unroll
;         for (int ai = 0; ai < 2; ++ai)
; #pragma unroll
;             for (int m = 0; m < 4; ++m) { const int row = row0 + ai * 128 + m * 16;
;                 float z[8]; unpack8(*(const u32x4*)(proj + (size_t)row * NIN + 5632 + col), z);
;                 float v[8];
; #pragma unroll
;                 for (int e = 0; e < 4; ++e) { v[e] = acc[ai][0][m][0][e] * sigmoidf_(acc[ai][1][m][0][e]) * z[e]; v[4 + e] = acc[ai][0][m][1][e] * sigmoidf_(acc[ai][1][m][1][e]) * z[4 + e]; }
;                 *(u32x4*)(U + (size_t)row * DM + 1536 + col) = pack8(v); }
;     }
	v_mul_f32_e32 v65, 0xbfb8aa3b, v70
	v_exp_f32_e32 v65, v65
	v_mul_f32_e32 v64, 0xbfb8aa3b, v78
	v_exp_f32_e32 v64, v64
	v_lshlrev_b32_e32 v76, 16, v83
	v_add_f32_e32 v65, 1.0, v65
	v_rcp_f32_e32 v70, v65
	v_mul_f32_e32 v65, 0xbfb8aa3b, v79
	v_exp_f32_e32 v65, v65
	v_add_f32_e32 v64, 1.0, v64
	v_rcp_f32_e32 v64, v64
	v_and_b32_e32 v77, 0xffff0000, v83
	v_add_f32_e32 v65, 1.0, v65
	v_rcp_f32_e32 v65, v65
	v_lshlrev_b32_e32 v86, 16, v82
	v_and_b32_e32 v87, 0xffff0000, v82
	v_pk_mul_f32 v[72:73], v[72:73], v[86:87]
	v_pk_mul_f32 v[64:65], v[64:65], v[74:75]
	s_nop 0
	v_pk_mul_f32 v[74:75], v[64:65], v[76:77]
	v_mul_f32_e32 v64, 0xbfb8aa3b, v71
	v_exp_f32_e32 v64, v64
	v_and_b32_e32 v65, 0xffff0000, v85
	v_add_f32_e32 v64, 1.0, v64
	v_rcp_f32_e32 v71, v64
	v_lshlrev_b32_e32 v64, 16, v85
	v_pk_mul_f32 v[66:67], v[70:71], v[66:67]
	s_nop 0
	v_pk_mul_f32 v[70:71], v[66:67], v[64:65]
	v_cvt_pk_bf16_f32 v66, v68, v69
	v_lshlrev_b64 v[68:69], 12, v[80:81]
	v_lshl_add_u64 v[68:69], s[8:9], 0, v[68:69]
	v_cvt_pk_bf16_f32 v64, v72, v73
	v_cvt_pk_bf16_f32 v65, v74, v75
	v_cvt_pk_bf16_f32 v67, v70, v71
	v_lshl_add_u64 v[68:69], v[68:69], 0, v[138:139]
	global_store_dwordx4 v[68:69], v[64:67], off offset:3072
	s_nop 1
	v_add_u32_e32 v64, 0x80, v140
	v_mad_i64_i32 v[66:67], s[24:25], v64, s68, v[142:143]
	v_lshl_add_u64 v[66:67], v[66:67], 0, v[138:139]
	v_add_co_u32_e32 v66, vcc, s91, v66
	v_ashrrev_i32_e32 v65, 31, v64
	s_nop 0
	v_addc_co_u32_e32 v67, vcc, 0, v67, vcc
	v_mov_b64_e32 v[66:67], v[178:179]
	v_mov_b64_e32 v[68:69], v[180:181]
	s_nop 0
	v_lshlrev_b32_e32 v60, 16, v68
	v_and_b32_e32 v61, 0xffff0000, v68
	v_pk_mul_f32 v[52:53], v[48:49], v[60:61]
	v_mul_f32_e32 v49, 0xbfb8aa3b, v54
	v_exp_f32_e32 v49, v49
	v_mul_f32_e32 v48, 0xbfb8aa3b, v62
	v_exp_f32_e32 v48, v48
	v_lshlrev_b32_e32 v60, 16, v67
	v_add_f32_e32 v49, 1.0, v49
	v_rcp_f32_e32 v54, v49
	v_mul_f32_e32 v49, 0xbfb8aa3b, v63
	v_exp_f32_e32 v49, v49
	v_add_f32_e32 v48, 1.0, v48
	v_rcp_f32_e32 v48, v48
	v_and_b32_e32 v61, 0xffff0000, v67
	v_add_f32_e32 v49, 1.0, v49
	v_rcp_f32_e32 v49, v49
	v_lshlrev_b32_e32 v70, 16, v66
	v_and_b32_e32 v71, 0xffff0000, v66
	v_pk_mul_f32 v[56:57], v[56:57], v[70:71]
	v_pk_mul_f32 v[48:49], v[48:49], v[58:59]
	s_nop 0
	v_pk_mul_f32 v[58:59], v[48:49], v[60:61]
	v_mul_f32_e32 v48, 0xbfb8aa3b, v55
	v_exp_f32_e32 v48, v48
	v_and_b32_e32 v49, 0xffff0000, v69
	v_add_f32_e32 v48, 1.0, v48
	v_rcp_f32_e32 v55, v48
	v_lshlrev_b32_e32 v48, 16, v69
	v_pk_mul_f32 v[50:51], v[54:55], v[50:51]
	s_nop 0
	v_pk_mul_f32 v[54:55], v[50:51], v[48:49]
	v_cvt_pk_bf16_f32 v50, v52, v53
	v_lshlrev_b64 v[52:53], 12, v[64:65]
	v_lshl_add_u64 v[52:53], s[8:9], 0, v[52:53]
	v_cvt_pk_bf16_f32 v48, v56, v57
	v_cvt_pk_bf16_f32 v49, v58, v59
	v_cvt_pk_bf16_f32 v51, v54, v55
	v_lshl_add_u64 v[52:53], v[52:53], 0, v[138:139]
	global_store_dwordx4 v[52:53], v[48:51], off offset:3072
	s_nop 1
	v_add_u32_e32 v48, 0x90, v140
	v_mad_i64_i32 v[50:51], s[24:25], v48, s68, v[142:143]
	v_lshl_add_u64 v[50:51], v[50:51], 0, v[138:139]
	v_add_co_u32_e32 v50, vcc, s91, v50
	v_ashrrev_i32_e32 v49, 31, v48
	s_nop 0
	v_addc_co_u32_e32 v51, vcc, 0, v51, vcc
	v_mov_b64_e32 v[50:51], v[182:183]
	v_mov_b64_e32 v[52:53], v[184:185]
	s_nop 0
	v_lshlrev_b32_e32 v44, 16, v52
	v_and_b32_e32 v45, 0xffff0000, v52
	v_pk_mul_f32 v[36:37], v[32:33], v[44:45]
	v_mul_f32_e32 v33, 0xbfb8aa3b, v38
	v_exp_f32_e32 v33, v33
	v_mul_f32_e32 v32, 0xbfb8aa3b, v46
	v_exp_f32_e32 v32, v32
	v_lshlrev_b32_e32 v44, 16, v51
	v_add_f32_e32 v33, 1.0, v33
	v_rcp_f32_e32 v38, v33
	v_mul_f32_e32 v33, 0xbfb8aa3b, v47
	v_exp_f32_e32 v33, v33
	v_add_f32_e32 v32, 1.0, v32
	v_rcp_f32_e32 v32, v32
	v_and_b32_e32 v45, 0xffff0000, v51
	v_add_f32_e32 v33, 1.0, v33
	v_rcp_f32_e32 v33, v33
	v_lshlrev_b32_e32 v54, 16, v50
	v_and_b32_e32 v55, 0xffff0000, v50
	v_pk_mul_f32 v[40:41], v[40:41], v[54:55]
	v_pk_mul_f32 v[32:33], v[32:33], v[42:43]
	s_nop 0
	v_pk_mul_f32 v[42:43], v[32:33], v[44:45]
; __device__ __forceinline__ float sigmoidf_(float x) { return __builtin_amdgcn_rcpf(1.0f + __builtin_amdgcn_exp2f(-1.4426950408889634f * x)); }
; __device__ __forceinline__ void unpack8(const u32x4 w, float (&f)[8]) { f[0] = bflo(w.x); f[1] = bfhi(w.x); f[2] = bflo(w.y); f[3] = bfhi(w.y); f[4] = bflo(w.z); f[5] = bfhi(w.z); f[6] = bflo(w.w); f[7] = bfhi(w.w); }
; __device__ __forceinline__ u32x4 pack8(const float (&f)[8]) { u32x4 w; w.x = cvt_pk_bf16(f[0], f[1]); w.y = cvt_pk_bf16(f[2], f[3]); w.z = cvt_pk_bf16(f[4], f[5]); w.w = cvt_pk_bf16(f[6], f[7]); return w; }
;     __device__ __forceinline__ void operator()(const Acc& acc, const Unit& u, int wr, int wc, int fr, int fq) const {
;         const int row0 = u.pm * 256 + wr * 64 + fr, col = u.pn * 128 + wc * 32 + 8 * fq;
; #pragma unroll
;         for (int ai = 0; ai < 2; ++ai)
; #pragma unroll
;             for (int m = 0; m < 4; ++m) { const int row = row0 + ai * 128 + m * 16;
;                 float z[8]; unpack8(*(const u32x4*)(proj + (size_t)row * NIN + 5632 + col), z);
;                 float v[8];
; #pragma unroll
;                 for (int e = 0; e < 4; ++e) { v[e] = acc[ai][0][m][0][e] * sigmoidf_(acc[ai][1][m][0][e]) * z[e]; v[4 + e] = acc[ai][0][m][1][e] * sigmoidf_(acc[ai][1][m][1][e]) * z[4 + e]; }
;                 *(u32x4*)(U + (size_t)row * DM + 1536 + col) = pack8(v); }
;     }
	v_mul_f32_e32 v32, 0xbfb8aa3b, v39
	v_exp_f32_e32 v32, v32
	v_and_b32_e32 v33, 0xffff0000, v53
	v_add_f32_e32 v32, 1.0, v32
	v_rcp_f32_e32 v39, v32
	v_lshlrev_b32_e32 v32, 16, v53
	v_pk_mul_f32 v[34:35], v[38:39], v[34:35]
	s_nop 0
	v_pk_mul_f32 v[38:39], v[34:35], v[32:33]
	v_cvt_pk_bf16_f32 v34, v36, v37
	v_lshlrev_b64 v[36:37], 12, v[48:49]
	v_lshl_add_u64 v[36:37], s[8:9], 0, v[36:37]
	v_cvt_pk_bf16_f32 v32, v40, v41
	v_cvt_pk_bf16_f32 v33, v42, v43
	v_cvt_pk_bf16_f32 v35, v38, v39
	v_lshl_add_u64 v[36:37], v[36:37], 0, v[138:139]
	global_store_dwordx4 v[36:37], v[32:35], off offset:3072
	s_nop 1
	v_add_u32_e32 v32, 0xa0, v140
	v_mad_i64_i32 v[34:35], s[24:25], v32, s68, v[142:143]
	v_lshl_add_u64 v[34:35], v[34:35], 0, v[138:139]
	v_add_co_u32_e32 v34, vcc, s91, v34
	v_ashrrev_i32_e32 v33, 31, v32
	s_nop 0
	v_addc_co_u32_e32 v35, vcc, 0, v35, vcc
	v_mov_b64_e32 v[34:35], v[186:187]
	v_mov_b64_e32 v[36:37], v[188:189]
	s_nop 0
	v_lshlrev_b32_e32 v28, 16, v36
	v_and_b32_e32 v29, 0xffff0000, v36
	v_pk_mul_f32 v[20:21], v[16:17], v[28:29]
	v_mul_f32_e32 v17, 0xbfb8aa3b, v22
	v_exp_f32_e32 v17, v17
	v_mul_f32_e32 v16, 0xbfb8aa3b, v30
	v_exp_f32_e32 v16, v16
	v_lshlrev_b32_e32 v28, 16, v35
	v_add_f32_e32 v17, 1.0, v17
	v_rcp_f32_e32 v22, v17
	v_mul_f32_e32 v17, 0xbfb8aa3b, v31
	v_exp_f32_e32 v17, v17
	v_add_f32_e32 v16, 1.0, v16
	v_rcp_f32_e32 v16, v16
	v_and_b32_e32 v29, 0xffff0000, v35
	v_add_f32_e32 v17, 1.0, v17
	v_rcp_f32_e32 v17, v17
	v_lshlrev_b32_e32 v38, 16, v34
	v_and_b32_e32 v39, 0xffff0000, v34
	v_pk_mul_f32 v[24:25], v[24:25], v[38:39]
	v_pk_mul_f32 v[16:17], v[16:17], v[26:27]
	s_nop 0
	v_pk_mul_f32 v[26:27], v[16:17], v[28:29]
	v_mul_f32_e32 v16, 0xbfb8aa3b, v23
	v_exp_f32_e32 v16, v16
	v_and_b32_e32 v17, 0xffff0000, v37
	v_add_f32_e32 v16, 1.0, v16
	v_rcp_f32_e32 v23, v16
	v_lshlrev_b32_e32 v16, 16, v37
	v_pk_mul_f32 v[18:19], v[22:23], v[18:19]
	s_nop 0
	v_pk_mul_f32 v[22:23], v[18:19], v[16:17]
	v_cvt_pk_bf16_f32 v18, v20, v21
	v_lshlrev_b64 v[20:21], 12, v[32:33]
	v_lshl_add_u64 v[20:21], s[8:9], 0, v[20:21]
	v_cvt_pk_bf16_f32 v16, v24, v25
	v_cvt_pk_bf16_f32 v17, v26, v27
	v_cvt_pk_bf16_f32 v19, v22, v23
	v_lshl_add_u64 v[20:21], v[20:21], 0, v[138:139]
	global_store_dwordx4 v[20:21], v[16:19], off offset:3072
	s_nop 1
	v_add_u32_e32 v16, 0xb0, v140
	v_mad_i64_i32 v[18:19], s[24:25], v16, s68, v[142:143]
	v_lshl_add_u64 v[18:19], v[18:19], 0, v[138:139]
	v_add_co_u32_e32 v18, vcc, s91, v18
	v_ashrrev_i32_e32 v17, 31, v16
	s_nop 0
	v_addc_co_u32_e32 v19, vcc, 0, v19, vcc
	v_mov_b64_e32 v[18:19], v[210:211]
	v_mov_b64_e32 v[20:21], v[212:213]
	s_and_b64 vcc, exec, s[20:21]
	s_mov_b64 s[24:25], s[16:17]
	s_nop 0
	v_lshlrev_b32_e32 v12, 16, v20
	v_and_b32_e32 v13, 0xffff0000, v20
	v_pk_mul_f32 v[4:5], v[0:1], v[12:13]
	v_mul_f32_e32 v1, 0xbfb8aa3b, v6
	v_exp_f32_e32 v1, v1
	v_mul_f32_e32 v0, 0xbfb8aa3b, v14
	v_exp_f32_e32 v0, v0
	v_lshlrev_b32_e32 v12, 16, v19
	v_add_f32_e32 v1, 1.0, v1
	v_rcp_f32_e32 v6, v1
	v_mul_f32_e32 v1, 0xbfb8aa3b, v15
	v_exp_f32_e32 v1, v1
	v_add_f32_e32 v0, 1.0, v0
	v_rcp_f32_e32 v0, v0
	v_and_b32_e32 v13, 0xffff0000, v19
	v_add_f32_e32 v1, 1.0, v1
	v_rcp_f32_e32 v1, v1
	v_lshlrev_b32_e32 v22, 16, v18
	v_and_b32_e32 v23, 0xffff0000, v18
	v_pk_mul_f32 v[8:9], v[8:9], v[22:23]
	v_pk_mul_f32 v[0:1], v[0:1], v[10:11]
	s_nop 0
	v_pk_mul_f32 v[10:11], v[0:1], v[12:13]
	v_mul_f32_e32 v0, 0xbfb8aa3b, v7
	v_exp_f32_e32 v0, v0
	v_and_b32_e32 v1, 0xffff0000, v21
	v_add_f32_e32 v0, 1.0, v0
	v_rcp_f32_e32 v7, v0
	v_lshlrev_b32_e32 v0, 16, v21
	v_pk_mul_f32 v[2:3], v[6:7], v[2:3]
	s_nop 0
	v_pk_mul_f32 v[6:7], v[2:3], v[0:1]
	v_cvt_pk_bf16_f32 v2, v4, v5
	v_lshlrev_b64 v[4:5], 12, v[16:17]
	v_lshl_add_u64 v[4:5], s[8:9], 0, v[4:5]
	v_cvt_pk_bf16_f32 v0, v8, v9
	v_cvt_pk_bf16_f32 v1, v10, v11
	v_cvt_pk_bf16_f32 v3, v6, v7
	v_lshl_add_u64 v[4:5], v[4:5], 0, v[138:139]
	global_store_dwordx4 v[4:5], v[0:3], off offset:3072
	s_cbranch_vccnz .LBB0_316

; __device__ __forceinline__ float sigmoidf_(float x) { return __builtin_amdgcn_rcpf(1.0f + __builtin_amdgcn_exp2f(-1.4426950408889634f * x)); }
; __device__ __forceinline__ float siluf_(float x) { return x * sigmoidf_(x); }
;     __device__ __forceinline__ void operator()(const Acc& acc, const Unit& u, int wr, int wc, int fr, int fq) const {
;     ...
;         int mode = 0;
;         if (pn < 2) mode = 1; else if (pn == 6 || pn == 7 || pn == 10 || pn == 11 || pn == 18 || pn == 19 || pn == 22 || pn == 23) mode = 2;
;         else if (pn == 20 || pn == 21) mode = 3; else if (pn >= 24) mode = 4;
; #pragma unroll
;         for (int bj = 0; bj < 2; ++bj) {
;             const int col = col0 + bj * 128;
;             float bg[8];
; #pragma unroll
;             for (int e = 0; e < 8; ++e) bg[e] = 0.f;
;             if (mode == 4) { const f32x4 b0 = *(const f32x4*)(bgate + col - 6144), b1 = *(const f32x4*)(bgate + col - 6144 + 4);
; #pragma unroll
;                 for (int e = 0; e < 4; ++e) { bg[e] = b0[e]; bg[4 + e] = b1[e]; } }
; #pragma unroll
;             for (int ai = 0; ai < 2; ++ai)
; #pragma unroll
;                 for (int m = 0; m < 4; ++m) {
;                     const int row = row0 + ai * 128 + m * 16;
;                     float v[8];
; #pragma unroll
;                     for (int e = 0; e < 4; ++e) { v[e] = acc[ai][bj][m][0][e]; v[4 + e] = acc[ai][bj][m][1][e]; }
;                     if (mode == 1) {
; #pragma unroll
;                         for (int e = 0; e < 8; ++e) v[e] *= 0.125f;
;                     } else if (mode == 2) {
; #pragma unroll
;                         for (int e = 0; e < 8; ++e) v[e] = siluf_(v[e]);
;                     } else if (mode == 4) {
; #pragma unroll
;                         for (int e = 0; e < 8; ++e) v[e] = sigmoidf_(v[e] + bg[e]);
;                     }
;                     const u32x4 w = pack8(v);
;                     if (mode == 3) { const int cc = col - 5120, g = cc >> 4, h0 = cc & 15, n = row >> 4, j = row & 15;
;                         *(u32x4*)(X + ((size_t)(g * XROWS + n) * 512 + j * 16 + h0)) = w; }
;                     else *(u32x4*)(proj + (size_t)row * NIN + col) = w;
;                 }
;         }
.LBB0_552:
	s_lshl_b32 s51, s43, 8
	s_add_i32 s51, s51, s18
	v_or_b32_e32 v214, s51, v209
	v_lshl_or_b32 v168, s4, 8, v212
	s_cmp_lg_u32 s42, 1
	s_mov_b64 s[6:7], -1
	s_cbranch_scc0 .LBB0_724
	s_cmp_lt_i32 s4, 24
	s_cbranch_scc0 .LBB0_721
	s_and_b32 s6, s4, 0x7ffffffe
	s_cmp_eq_u32 s6, 20
	s_cbranch_scc1 .Lepi_orig
	s_mov_b32 s6, 0xcc0cc0
	s_bitcmp1_b32 s6, s4
	s_cbranch_scc1 .Lepi_silu
	s_cmp_lt_i32 s4, 2
	s_cbranch_scc1 .Lepi_q
	v_ashrrev_i32_e32 v169, 31, v168
	v_mov_b64_e32 v[132:133], s[14:15]
	v_mad_i64_i32 v[132:133], s[8:9], v214, s68, v[132:133]
	v_lshl_add_u64 v[132:133], v[168:169], 1, v[132:133]
	v_mov_b64_e32 v[134:135], v[132:133]
	v_cvt_pk_bf16_f32 v128, v120, v121
	v_cvt_pk_bf16_f32 v129, v122, v123
	v_cvt_pk_bf16_f32 v130, v124, v125
	v_cvt_pk_bf16_f32 v131, v126, v127
	global_store_dwordx4 v[134:135], v[128:131], off
	v_cvt_pk_bf16_f32 v136, v116, v117
	v_cvt_pk_bf16_f32 v137, v118, v119
	v_cvt_pk_bf16_f32 v138, v112, v113
	v_cvt_pk_bf16_f32 v139, v114, v115
	global_store_dwordx4 v[134:135], v[136:139], off offset:256
	s_mov_b64 s[8:9], 0x70000
	s_nop 0
	v_lshl_add_u64 v[174:175], v[132:133], 0, s[8:9]
	v_cvt_pk_bf16_f32 v140, v108, v109
	v_cvt_pk_bf16_f32 v141, v110, v111
	v_cvt_pk_bf16_f32 v142, v104, v105
	v_cvt_pk_bf16_f32 v143, v106, v107
	global_store_dwordx4 v[174:175], v[140:143], off
	v_cvt_pk_bf16_f32 v170, v100, v101
	v_cvt_pk_bf16_f32 v171, v102, v103
	v_cvt_pk_bf16_f32 v172, v96, v97
	v_cvt_pk_bf16_f32 v173, v98, v99
	global_store_dwordx4 v[174:175], v[170:173], off offset:256
	s_mov_b64 s[8:9], 0xe0000
	s_nop 0
	v_lshl_add_u64 v[134:135], v[132:133], 0, s[8:9]
	v_cvt_pk_bf16_f32 v128, v92, v93
	v_cvt_pk_bf16_f32 v129, v94, v95
	v_cvt_pk_bf16_f32 v130, v88, v89
	v_cvt_pk_bf16_f32 v131, v90, v91
	global_store_dwordx4 v[134:135], v[128:131], off
	v_cvt_pk_bf16_f32 v136, v84, v85
	v_cvt_pk_bf16_f32 v137, v86, v87
	v_cvt_pk_bf16_f32 v138, v80, v81
	v_cvt_pk_bf16_f32 v139, v82, v83
	global_store_dwordx4 v[134:135], v[136:139], off offset:256
	s_mov_b64 s[8:9], 0x150000
	s_nop 0
	v_lshl_add_u64 v[174:175], v[132:133], 0, s[8:9]
	v_cvt_pk_bf16_f32 v140, v76, v77
	v_cvt_pk_bf16_f32 v141, v78, v79
	v_cvt_pk_bf16_f32 v142, v72, v73
	v_cvt_pk_bf16_f32 v143, v74, v75
	global_store_dwordx4 v[174:175], v[140:143], off
	v_cvt_pk_bf16_f32 v170, v68, v69
	v_cvt_pk_bf16_f32 v171, v70, v71
	v_cvt_pk_bf16_f32 v172, v64, v65
	v_cvt_pk_bf16_f32 v173, v66, v67
	global_store_dwordx4 v[174:175], v[170:173], off offset:256
	s_mov_b64 s[8:9], 0x380000
	s_nop 0
	v_lshl_add_u64 v[134:135], v[132:133], 0, s[8:9]
	v_cvt_pk_bf16_f32 v128, v60, v61
	v_cvt_pk_bf16_f32 v129, v62, v63
	v_cvt_pk_bf16_f32 v130, v56, v57
	v_cvt_pk_bf16_f32 v131, v58, v59
	global_store_dwordx4 v[134:135], v[128:131], off
	v_cvt_pk_bf16_f32 v136, v52, v53
	v_cvt_pk_bf16_f32 v137, v54, v55
	v_cvt_pk_bf16_f32 v138, v48, v49
	v_cvt_pk_bf16_f32 v139, v50, v51
	global_store_dwordx4 v[134:135], v[136:139], off offset:256
	s_mov_b64 s[8:9], 0x3f0000
	s_nop 0
	v_lshl_add_u64 v[174:175], v[132:133], 0, s[8:9]
	v_cvt_pk_bf16_f32 v140, v44, v45
	v_cvt_pk_bf16_f32 v141, v46, v47
	v_cvt_pk_bf16_f32 v142, v40, v41
	v_cvt_pk_bf16_f32 v143, v42, v43
	global_store_dwordx4 v[174:175], v[140:143], off
	v_cvt_pk_bf16_f32 v170, v36, v37
	v_cvt_pk_bf16_f32 v171, v38, v39
	v_cvt_pk_bf16_f32 v172, v32, v33
	v_cvt_pk_bf16_f32 v173, v34, v35
	global_store_dwordx4 v[174:175], v[170:173], off offset:256
	s_mov_b64 s[8:9], 0x460000
	s_nop 0
	v_lshl_add_u64 v[134:135], v[132:133], 0, s[8:9]
	v_cvt_pk_bf16_f32 v128, v28, v29
	v_cvt_pk_bf16_f32 v129, v30, v31
	v_cvt_pk_bf16_f32 v130, v24, v25
	v_cvt_pk_bf16_f32 v131, v26, v27
	global_store_dwordx4 v[134:135], v[128:131], off
	v_cvt_pk_bf16_f32 v136, v20, v21
	v_cvt_pk_bf16_f32 v137, v22, v23
	v_cvt_pk_bf16_f32 v138, v16, v17
	v_cvt_pk_bf16_f32 v139, v18, v19
	global_store_dwordx4 v[134:135], v[136:139], off offset:256
	s_mov_b64 s[8:9], 0x4d0000
	s_nop 0
	v_lshl_add_u64 v[174:175], v[132:133], 0, s[8:9]
	v_cvt_pk_bf16_f32 v140, v12, v13
	v_cvt_pk_bf16_f32 v141, v14, v15
	v_cvt_pk_bf16_f32 v142, v8, v9
	v_cvt_pk_bf16_f32 v143, v10, v11
	global_store_dwordx4 v[174:175], v[140:143], off
	v_cvt_pk_bf16_f32 v170, v4, v5
	v_cvt_pk_bf16_f32 v171, v6, v7
	v_cvt_pk_bf16_f32 v172, v0, v1
	v_cvt_pk_bf16_f32 v173, v2, v3
	global_store_dwordx4 v[174:175], v[170:173], off offset:256
	s_branch .LBB0_723
; __device__ __forceinline__ float sigmoidf_(float x) { return __builtin_amdgcn_rcpf(1.0f + __builtin_amdgcn_exp2f(-1.4426950408889634f * x)); }
; __device__ __forceinline__ float siluf_(float x) { return x * sigmoidf_(x); }
; __device__ __forceinline__ u32x4 pack8(const float (&f)[8]) { u32x4 w; w.x = cvt_pk_bf16(f[0], f[1]); w.y = cvt_pk_bf16(f[2], f[3]); w.z = cvt_pk_bf16(f[4], f[5]); w.w = cvt_pk_bf16(f[6], f[7]); return w; }
;     __device__ __forceinline__ void operator()(const Acc& acc, const Unit& u, int wr, int wc, int fr, int fq) const {
;     ...
;                     if (mode == 1) {
; #pragma unroll
;                         for (int e = 0; e < 8; ++e) v[e] *= 0.125f;
;                     } else if (mode == 2) {
; #pragma unroll
;                         for (int e = 0; e < 8; ++e) v[e] = siluf_(v[e]);
;                     } else if (mode == 4) {
; #pragma unroll
;                         for (int e = 0; e < 8; ++e) v[e] = sigmoidf_(v[e] + bg[e]);
;                     }
;                     const u32x4 w = pack8(v);
;                     if (mode == 3) { const int cc = col - 5120, g = cc >> 4, h0 = cc & 15, n = row >> 4, j = row & 15;
;                         *(u32x4*)(X + ((size_t)(g * XROWS + n) * 512 + j * 16 + h0)) = w; }
;                     else *(u32x4*)(proj + (size_t)row * NIN + col) = w;
.Lepi_q:
	s_mov_b32 s10, 0x3e000000
	v_ashrrev_i32_e32 v169, 31, v168
	v_mov_b64_e32 v[132:133], s[14:15]
	v_mad_i64_i32 v[132:133], s[8:9], v214, s68, v[132:133]
	v_lshl_add_u64 v[132:133], v[168:169], 1, v[132:133]
	v_mov_b64_e32 v[134:135], v[132:133]
	v_pk_mul_f32 v[176:177], v[120:121], s[10:11] op_sel_hi:[1,0]
	v_pk_mul_f32 v[178:179], v[122:123], s[10:11] op_sel_hi:[1,0]
	v_pk_mul_f32 v[180:181], v[124:125], s[10:11] op_sel_hi:[1,0]
	v_pk_mul_f32 v[182:183], v[126:127], s[10:11] op_sel_hi:[1,0]
	v_cvt_pk_bf16_f32 v128, v176, v177
	v_cvt_pk_bf16_f32 v129, v178, v179
	v_cvt_pk_bf16_f32 v130, v180, v181
	v_cvt_pk_bf16_f32 v131, v182, v183
	global_store_dwordx4 v[134:135], v[128:131], off
	v_pk_mul_f32 v[216:217], v[116:117], s[10:11] op_sel_hi:[1,0]
	v_pk_mul_f32 v[218:219], v[118:119], s[10:11] op_sel_hi:[1,0]
	v_pk_mul_f32 v[220:221], v[112:113], s[10:11] op_sel_hi:[1,0]
	v_pk_mul_f32 v[222:223], v[114:115], s[10:11] op_sel_hi:[1,0]
	v_cvt_pk_bf16_f32 v136, v216, v217
	v_cvt_pk_bf16_f32 v137, v218, v219
	v_cvt_pk_bf16_f32 v138, v220, v221
	v_cvt_pk_bf16_f32 v139, v222, v223
	global_store_dwordx4 v[134:135], v[136:139], off offset:256
	s_mov_b64 s[8:9], 0x70000
	s_nop 0
	v_lshl_add_u64 v[174:175], v[132:133], 0, s[8:9]
	v_pk_mul_f32 v[176:177], v[108:109], s[10:11] op_sel_hi:[1,0]
	v_pk_mul_f32 v[178:179], v[110:111], s[10:11] op_sel_hi:[1,0]
	v_pk_mul_f32 v[180:181], v[104:105], s[10:11] op_sel_hi:[1,0]
	v_pk_mul_f32 v[182:183], v[106:107], s[10:11] op_sel_hi:[1,0]
	v_cvt_pk_bf16_f32 v140, v176, v177
	v_cvt_pk_bf16_f32 v141, v178, v179
	v_cvt_pk_bf16_f32 v142, v180, v181
	v_cvt_pk_bf16_f32 v143, v182, v183
	global_store_dwordx4 v[174:175], v[140:143], off
	v_pk_mul_f32 v[216:217], v[100:101], s[10:11] op_sel_hi:[1,0]
	v_pk_mul_f32 v[218:219], v[102:103], s[10:11] op_sel_hi:[1,0]
	v_pk_mul_f32 v[220:221], v[96:97], s[10:11] op_sel_hi:[1,0]
	v_pk_mul_f32 v[222:223], v[98:99], s[10:11] op_sel_hi:[1,0]
	v_cvt_pk_bf16_f32 v170, v216, v217
	v_cvt_pk_bf16_f32 v171, v218, v219
	v_cvt_pk_bf16_f32 v172, v220, v221
	v_cvt_pk_bf16_f32 v173, v222, v223
	global_store_dwordx4 v[174:175], v[170:173], off offset:256
	s_mov_b64 s[8:9], 0xe0000
	s_nop 0
	v_lshl_add_u64 v[134:135], v[132:133], 0, s[8:9]
	v_pk_mul_f32 v[176:177], v[92:93], s[10:11] op_sel_hi:[1,0]
	v_pk_mul_f32 v[178:179], v[94:95], s[10:11] op_sel_hi:[1,0]
	v_pk_mul_f32 v[180:181], v[88:89], s[10:11] op_sel_hi:[1,0]
	v_pk_mul_f32 v[182:183], v[90:91], s[10:11] op_sel_hi:[1,0]
	v_cvt_pk_bf16_f32 v128, v176, v177
	v_cvt_pk_bf16_f32 v129, v178, v179
	v_cvt_pk_bf16_f32 v130, v180, v181
	v_cvt_pk_bf16_f32 v131, v182, v183
	global_store_dwordx4 v[134:135], v[128:131], off
	v_pk_mul_f32 v[216:217], v[84:85], s[10:11] op_sel_hi:[1,0]
	v_pk_mul_f32 v[218:219], v[86:87], s[10:11] op_sel_hi:[1,0]
	v_pk_mul_f32 v[220:221], v[80:81], s[10:11] op_sel_hi:[1,0]
	v_pk_mul_f32 v[222:223], v[82:83], s[10:11] op_sel_hi:[1,0]
	v_cvt_pk_bf16_f32 v136, v216, v217
	v_cvt_pk_bf16_f32 v137, v218, v219
	v_cvt_pk_bf16_f32 v138, v220, v221
	v_cvt_pk_bf16_f32 v139, v222, v223
	global_store_dwordx4 v[134:135], v[136:139], off offset:256
	s_mov_b64 s[8:9], 0x150000
	s_nop 0
	v_lshl_add_u64 v[174:175], v[132:133], 0, s[8:9]
	v_pk_mul_f32 v[176:177], v[76:77], s[10:11] op_sel_hi:[1,0]
	v_pk_mul_f32 v[178:179], v[78:79], s[10:11] op_sel_hi:[1,0]
	v_pk_mul_f32 v[180:181], v[72:73], s[10:11] op_sel_hi:[1,0]
	v_pk_mul_f32 v[182:183], v[74:75], s[10:11] op_sel_hi:[1,0]
	v_cvt_pk_bf16_f32 v140, v176, v177
	v_cvt_pk_bf16_f32 v141, v178, v179
	v_cvt_pk_bf16_f32 v142, v180, v181
	v_cvt_pk_bf16_f32 v143, v182, v183
	global_store_dwordx4 v[174:175], v[140:143], off
	v_pk_mul_f32 v[216:217], v[68:69], s[10:11] op_sel_hi:[1,0]
	v_pk_mul_f32 v[218:219], v[70:71], s[10:11] op_sel_hi:[1,0]
	v_pk_mul_f32 v[220:221], v[64:65], s[10:11] op_sel_hi:[1,0]
	v_pk_mul_f32 v[222:223], v[66:67], s[10:11] op_sel_hi:[1,0]
	v_cvt_pk_bf16_f32 v170, v216, v217
	v_cvt_pk_bf16_f32 v171, v218, v219
	v_cvt_pk_bf16_f32 v172, v220, v221
	v_cvt_pk_bf16_f32 v173, v222, v223
	global_store_dwordx4 v[174:175], v[170:173], off offset:256
	s_mov_b64 s[8:9], 0x380000
	s_nop 0
	v_lshl_add_u64 v[134:135], v[132:133], 0, s[8:9]
	v_pk_mul_f32 v[176:177], v[60:61], s[10:11] op_sel_hi:[1,0]
	v_pk_mul_f32 v[178:179], v[62:63], s[10:11] op_sel_hi:[1,0]
	v_pk_mul_f32 v[180:181], v[56:57], s[10:11] op_sel_hi:[1,0]
	v_pk_mul_f32 v[182:183], v[58:59], s[10:11] op_sel_hi:[1,0]
	v_cvt_pk_bf16_f32 v128, v176, v177
	v_cvt_pk_bf16_f32 v129, v178, v179
	v_cvt_pk_bf16_f32 v130, v180, v181
	v_cvt_pk_bf16_f32 v131, v182, v183
	global_store_dwordx4 v[134:135], v[128:131], off
	v_pk_mul_f32 v[216:217], v[52:53], s[10:11] op_sel_hi:[1,0]
	v_pk_mul_f32 v[218:219], v[54:55], s[10:11] op_sel_hi:[1,0]
	v_pk_mul_f32 v[220:221], v[48:49], s[10:11] op_sel_hi:[1,0]
	v_pk_mul_f32 v[222:223], v[50:51], s[10:11] op_sel_hi:[1,0]
	v_cvt_pk_bf16_f32 v136, v216, v217
	v_cvt_pk_bf16_f32 v137, v218, v219
	v_cvt_pk_bf16_f32 v138, v220, v221
	v_cvt_pk_bf16_f32 v139, v222, v223
	global_store_dwordx4 v[134:135], v[136:139], off offset:256
	s_mov_b64 s[8:9], 0x3f0000
	s_nop 0
	v_lshl_add_u64 v[174:175], v[132:133], 0, s[8:9]
	v_pk_mul_f32 v[176:177], v[44:45], s[10:11] op_sel_hi:[1,0]
	v_pk_mul_f32 v[178:179], v[46:47], s[10:11] op_sel_hi:[1,0]
	v_pk_mul_f32 v[180:181], v[40:41], s[10:11] op_sel_hi:[1,0]
	v_pk_mul_f32 v[182:183], v[42:43], s[10:11] op_sel_hi:[1,0]
	v_cvt_pk_bf16_f32 v140, v176, v177
	v_cvt_pk_bf16_f32 v141, v178, v179
	v_cvt_pk_bf16_f32 v142, v180, v181
	v_cvt_pk_bf16_f32 v143, v182, v183
	global_store_dwordx4 v[174:175], v[140:143], off
	v_pk_mul_f32 v[216:217], v[36:37], s[10:11] op_sel_hi:[1,0]
; __device__ __forceinline__ float sigmoidf_(float x) { return __builtin_amdgcn_rcpf(1.0f + __builtin_amdgcn_exp2f(-1.4426950408889634f * x)); }
; __device__ __forceinline__ float siluf_(float x) { return x * sigmoidf_(x); }
; __device__ __forceinline__ u32x4 pack8(const float (&f)[8]) { u32x4 w; w.x = cvt_pk_bf16(f[0], f[1]); w.y = cvt_pk_bf16(f[2], f[3]); w.z = cvt_pk_bf16(f[4], f[5]); w.w = cvt_pk_bf16(f[6], f[7]); return w; }
;     __device__ __forceinline__ void operator()(const Acc& acc, const Unit& u, int wr, int wc, int fr, int fq) const {
;     ...
;                     if (mode == 1) {
; #pragma unroll
;                         for (int e = 0; e < 8; ++e) v[e] *= 0.125f;
;                     } else if (mode == 2) {
; #pragma unroll
;                         for (int e = 0; e < 8; ++e) v[e] = siluf_(v[e]);
;                     } else if (mode == 4) {
; #pragma unroll
;                         for (int e = 0; e < 8; ++e) v[e] = sigmoidf_(v[e] + bg[e]);
;                     }
;                     const u32x4 w = pack8(v);
	v_pk_mul_f32 v[218:219], v[38:39], s[10:11] op_sel_hi:[1,0]
	v_pk_mul_f32 v[220:221], v[32:33], s[10:11] op_sel_hi:[1,0]
	v_pk_mul_f32 v[222:223], v[34:35], s[10:11] op_sel_hi:[1,0]
	v_cvt_pk_bf16_f32 v170, v216, v217
	v_cvt_pk_bf16_f32 v171, v218, v219
	v_cvt_pk_bf16_f32 v172, v220, v221
	v_cvt_pk_bf16_f32 v173, v222, v223
	global_store_dwordx4 v[174:175], v[170:173], off offset:256
	s_mov_b64 s[8:9], 0x460000
	s_nop 0
	v_lshl_add_u64 v[134:135], v[132:133], 0, s[8:9]
	v_pk_mul_f32 v[176:177], v[28:29], s[10:11] op_sel_hi:[1,0]
	v_pk_mul_f32 v[178:179], v[30:31], s[10:11] op_sel_hi:[1,0]
	v_pk_mul_f32 v[180:181], v[24:25], s[10:11] op_sel_hi:[1,0]
	v_pk_mul_f32 v[182:183], v[26:27], s[10:11] op_sel_hi:[1,0]
	v_cvt_pk_bf16_f32 v128, v176, v177
	v_cvt_pk_bf16_f32 v129, v178, v179
	v_cvt_pk_bf16_f32 v130, v180, v181
	v_cvt_pk_bf16_f32 v131, v182, v183
	global_store_dwordx4 v[134:135], v[128:131], off
	v_pk_mul_f32 v[216:217], v[20:21], s[10:11] op_sel_hi:[1,0]
	v_pk_mul_f32 v[218:219], v[22:23], s[10:11] op_sel_hi:[1,0]
	v_pk_mul_f32 v[220:221], v[16:17], s[10:11] op_sel_hi:[1,0]
	v_pk_mul_f32 v[222:223], v[18:19], s[10:11] op_sel_hi:[1,0]
	v_cvt_pk_bf16_f32 v136, v216, v217
	v_cvt_pk_bf16_f32 v137, v218, v219
	v_cvt_pk_bf16_f32 v138, v220, v221
	v_cvt_pk_bf16_f32 v139, v222, v223
	global_store_dwordx4 v[134:135], v[136:139], off offset:256
	s_mov_b64 s[8:9], 0x4d0000
	s_nop 0
	v_lshl_add_u64 v[174:175], v[132:133], 0, s[8:9]
	v_pk_mul_f32 v[176:177], v[12:13], s[10:11] op_sel_hi:[1,0]
	v_pk_mul_f32 v[178:179], v[14:15], s[10:11] op_sel_hi:[1,0]
	v_pk_mul_f32 v[180:181], v[8:9], s[10:11] op_sel_hi:[1,0]
	v_pk_mul_f32 v[182:183], v[10:11], s[10:11] op_sel_hi:[1,0]
	v_cvt_pk_bf16_f32 v140, v176, v177
	v_cvt_pk_bf16_f32 v141, v178, v179
	v_cvt_pk_bf16_f32 v142, v180, v181
	v_cvt_pk_bf16_f32 v143, v182, v183
	global_store_dwordx4 v[174:175], v[140:143], off
	v_pk_mul_f32 v[216:217], v[4:5], s[10:11] op_sel_hi:[1,0]
	v_pk_mul_f32 v[218:219], v[6:7], s[10:11] op_sel_hi:[1,0]
	v_pk_mul_f32 v[220:221], v[0:1], s[10:11] op_sel_hi:[1,0]
	v_pk_mul_f32 v[222:223], v[2:3], s[10:11] op_sel_hi:[1,0]
	v_cvt_pk_bf16_f32 v170, v216, v217
	v_cvt_pk_bf16_f32 v171, v218, v219
	v_cvt_pk_bf16_f32 v172, v220, v221
	v_cvt_pk_bf16_f32 v173, v222, v223
	global_store_dwordx4 v[174:175], v[170:173], off offset:256
	s_branch .LBB0_723
.Lepi_silu:
	v_ashrrev_i32_e32 v169, 31, v168
	v_mov_b64_e32 v[132:133], s[14:15]
	v_mad_i64_i32 v[132:133], s[8:9], v214, s68, v[132:133]
	v_lshl_add_u64 v[132:133], v[168:169], 1, v[132:133]
	v_mov_b64_e32 v[134:135], v[132:133]
	v_mul_f32_e32 v176, 0xbfb8aa3b, v120
	v_mul_f32_e32 v177, 0xbfb8aa3b, v121
	v_mul_f32_e32 v178, 0xbfb8aa3b, v122
	v_mul_f32_e32 v179, 0xbfb8aa3b, v123
	v_mul_f32_e32 v180, 0xbfb8aa3b, v124
	v_mul_f32_e32 v181, 0xbfb8aa3b, v125
	v_mul_f32_e32 v182, 0xbfb8aa3b, v126
	v_mul_f32_e32 v183, 0xbfb8aa3b, v127
	v_exp_f32_e32 v176, v176
	v_exp_f32_e32 v177, v177
	v_exp_f32_e32 v178, v178
	v_exp_f32_e32 v179, v179
	v_exp_f32_e32 v180, v180
	v_exp_f32_e32 v181, v181
	v_exp_f32_e32 v182, v182
	v_exp_f32_e32 v183, v183
	v_add_f32_e32 v176, 1.0, v176
	v_add_f32_e32 v177, 1.0, v177
	v_add_f32_e32 v178, 1.0, v178
	v_add_f32_e32 v179, 1.0, v179
	v_add_f32_e32 v180, 1.0, v180
	v_add_f32_e32 v181, 1.0, v181
	v_add_f32_e32 v182, 1.0, v182
	v_add_f32_e32 v183, 1.0, v183
	v_rcp_f32_e32 v176, v176
	v_rcp_f32_e32 v177, v177
	v_rcp_f32_e32 v178, v178
	v_rcp_f32_e32 v179, v179
	v_rcp_f32_e32 v180, v180
	v_rcp_f32_e32 v181, v181
	v_rcp_f32_e32 v182, v182
	v_rcp_f32_e32 v183, v183
	v_pk_mul_f32 v[176:177], v[120:121], v[176:177]
	v_pk_mul_f32 v[178:179], v[122:123], v[178:179]
	v_pk_mul_f32 v[180:181], v[124:125], v[180:181]
	v_pk_mul_f32 v[182:183], v[126:127], v[182:183]
	v_cvt_pk_bf16_f32 v128, v176, v177
	v_cvt_pk_bf16_f32 v129, v178, v179
	v_cvt_pk_bf16_f32 v130, v180, v181
	v_cvt_pk_bf16_f32 v131, v182, v183
	global_store_dwordx4 v[134:135], v[128:131], off
	v_mul_f32_e32 v216, 0xbfb8aa3b, v116
	v_mul_f32_e32 v217, 0xbfb8aa3b, v117
	v_mul_f32_e32 v218, 0xbfb8aa3b, v118
	v_mul_f32_e32 v219, 0xbfb8aa3b, v119
	v_mul_f32_e32 v220, 0xbfb8aa3b, v112
	v_mul_f32_e32 v221, 0xbfb8aa3b, v113
	v_mul_f32_e32 v222, 0xbfb8aa3b, v114
	v_mul_f32_e32 v223, 0xbfb8aa3b, v115
	v_exp_f32_e32 v216, v216
	v_exp_f32_e32 v217, v217
	v_exp_f32_e32 v218, v218
	v_exp_f32_e32 v219, v219
	v_exp_f32_e32 v220, v220
	v_exp_f32_e32 v221, v221
	v_exp_f32_e32 v222, v222
	v_exp_f32_e32 v223, v223
	v_add_f32_e32 v216, 1.0, v216
	v_add_f32_e32 v217, 1.0, v217
	v_add_f32_e32 v218, 1.0, v218
	v_add_f32_e32 v219, 1.0, v219
	v_add_f32_e32 v220, 1.0, v220
	v_add_f32_e32 v221, 1.0, v221
	v_add_f32_e32 v222, 1.0, v222
	v_add_f32_e32 v223, 1.0, v223
	v_rcp_f32_e32 v216, v216
	v_rcp_f32_e32 v217, v217
	v_rcp_f32_e32 v218, v218
	v_rcp_f32_e32 v219, v219
	v_rcp_f32_e32 v220, v220
	v_rcp_f32_e32 v221, v221
	v_rcp_f32_e32 v222, v222
	v_rcp_f32_e32 v223, v223
	v_pk_mul_f32 v[216:217], v[116:117], v[216:217]
	v_pk_mul_f32 v[218:219], v[118:119], v[218:219]
	v_pk_mul_f32 v[220:221], v[112:113], v[220:221]
	v_pk_mul_f32 v[222:223], v[114:115], v[222:223]
	v_cvt_pk_bf16_f32 v136, v216, v217
	v_cvt_pk_bf16_f32 v137, v218, v219
	v_cvt_pk_bf16_f32 v138, v220, v221
	v_cvt_pk_bf16_f32 v139, v222, v223
	global_store_dwordx4 v[134:135], v[136:139], off offset:256
	s_mov_b64 s[8:9], 0x70000
	s_nop 0
	v_lshl_add_u64 v[174:175], v[132:133], 0, s[8:9]
	v_mul_f32_e32 v176, 0xbfb8aa3b, v108
	v_mul_f32_e32 v177, 0xbfb8aa3b, v109
	v_mul_f32_e32 v178, 0xbfb8aa3b, v110
	v_mul_f32_e32 v179, 0xbfb8aa3b, v111
	v_mul_f32_e32 v180, 0xbfb8aa3b, v104
	v_mul_f32_e32 v181, 0xbfb8aa3b, v105
	v_mul_f32_e32 v182, 0xbfb8aa3b, v106
; __device__ __forceinline__ u32x4 pack8(const float (&f)[8]) { u32x4 w; w.x = cvt_pk_bf16(f[0], f[1]); w.y = cvt_pk_bf16(f[2], f[3]); w.z = cvt_pk_bf16(f[4], f[5]); w.w = cvt_pk_bf16(f[6], f[7]); return w; }
; __device__ __forceinline__ float sigmoidf_(float x) { return __builtin_amdgcn_rcpf(1.0f + __builtin_amdgcn_exp2f(-1.4426950408889634f * x)); }
; __device__ __forceinline__ float siluf_(float x) { return x * sigmoidf_(x); }
;     __device__ __forceinline__ void operator()(const Acc& acc, const Unit& u, int wr, int wc, int fr, int fq) const {
;     ...
;                     } else if (mode == 2) {
; #pragma unroll
;                         for (int e = 0; e < 8; ++e) v[e] = siluf_(v[e]);
;                     } else if (mode == 4) {
; #pragma unroll
;                         for (int e = 0; e < 8; ++e) v[e] = sigmoidf_(v[e] + bg[e]);
;                     }
;                     const u32x4 w = pack8(v);
	v_mul_f32_e32 v183, 0xbfb8aa3b, v107
	v_exp_f32_e32 v176, v176
	v_exp_f32_e32 v177, v177
	v_exp_f32_e32 v178, v178
	v_exp_f32_e32 v179, v179
	v_exp_f32_e32 v180, v180
	v_exp_f32_e32 v181, v181
	v_exp_f32_e32 v182, v182
	v_exp_f32_e32 v183, v183
	v_add_f32_e32 v176, 1.0, v176
	v_add_f32_e32 v177, 1.0, v177
	v_add_f32_e32 v178, 1.0, v178
	v_add_f32_e32 v179, 1.0, v179
	v_add_f32_e32 v180, 1.0, v180
	v_add_f32_e32 v181, 1.0, v181
	v_add_f32_e32 v182, 1.0, v182
	v_add_f32_e32 v183, 1.0, v183
	v_rcp_f32_e32 v176, v176
	v_rcp_f32_e32 v177, v177
	v_rcp_f32_e32 v178, v178
	v_rcp_f32_e32 v179, v179
	v_rcp_f32_e32 v180, v180
	v_rcp_f32_e32 v181, v181
	v_rcp_f32_e32 v182, v182
	v_rcp_f32_e32 v183, v183
	v_pk_mul_f32 v[176:177], v[108:109], v[176:177]
	v_pk_mul_f32 v[178:179], v[110:111], v[178:179]
	v_pk_mul_f32 v[180:181], v[104:105], v[180:181]
	v_pk_mul_f32 v[182:183], v[106:107], v[182:183]
	v_cvt_pk_bf16_f32 v140, v176, v177
	v_cvt_pk_bf16_f32 v141, v178, v179
	v_cvt_pk_bf16_f32 v142, v180, v181
	v_cvt_pk_bf16_f32 v143, v182, v183
	global_store_dwordx4 v[174:175], v[140:143], off
	v_mul_f32_e32 v216, 0xbfb8aa3b, v100
	v_mul_f32_e32 v217, 0xbfb8aa3b, v101
	v_mul_f32_e32 v218, 0xbfb8aa3b, v102
	v_mul_f32_e32 v219, 0xbfb8aa3b, v103
	v_mul_f32_e32 v220, 0xbfb8aa3b, v96
	v_mul_f32_e32 v221, 0xbfb8aa3b, v97
	v_mul_f32_e32 v222, 0xbfb8aa3b, v98
	v_mul_f32_e32 v223, 0xbfb8aa3b, v99
	v_exp_f32_e32 v216, v216
	v_exp_f32_e32 v217, v217
	v_exp_f32_e32 v218, v218
	v_exp_f32_e32 v219, v219
	v_exp_f32_e32 v220, v220
	v_exp_f32_e32 v221, v221
	v_exp_f32_e32 v222, v222
	v_exp_f32_e32 v223, v223
	v_add_f32_e32 v216, 1.0, v216
	v_add_f32_e32 v217, 1.0, v217
	v_add_f32_e32 v218, 1.0, v218
	v_add_f32_e32 v219, 1.0, v219
	v_add_f32_e32 v220, 1.0, v220
	v_add_f32_e32 v221, 1.0, v221
	v_add_f32_e32 v222, 1.0, v222
	v_add_f32_e32 v223, 1.0, v223
	v_rcp_f32_e32 v216, v216
	v_rcp_f32_e32 v217, v217
	v_rcp_f32_e32 v218, v218
	v_rcp_f32_e32 v219, v219
	v_rcp_f32_e32 v220, v220
	v_rcp_f32_e32 v221, v221
	v_rcp_f32_e32 v222, v222
	v_rcp_f32_e32 v223, v223
	v_pk_mul_f32 v[216:217], v[100:101], v[216:217]
	v_pk_mul_f32 v[218:219], v[102:103], v[218:219]
	v_pk_mul_f32 v[220:221], v[96:97], v[220:221]
	v_pk_mul_f32 v[222:223], v[98:99], v[222:223]
	v_cvt_pk_bf16_f32 v170, v216, v217
	v_cvt_pk_bf16_f32 v171, v218, v219
	v_cvt_pk_bf16_f32 v172, v220, v221
	v_cvt_pk_bf16_f32 v173, v222, v223
	global_store_dwordx4 v[174:175], v[170:173], off offset:256
	s_mov_b64 s[8:9], 0xe0000
	s_nop 0
	v_lshl_add_u64 v[134:135], v[132:133], 0, s[8:9]
	v_mul_f32_e32 v176, 0xbfb8aa3b, v92
	v_mul_f32_e32 v177, 0xbfb8aa3b, v93
	v_mul_f32_e32 v178, 0xbfb8aa3b, v94
	v_mul_f32_e32 v179, 0xbfb8aa3b, v95
	v_mul_f32_e32 v180, 0xbfb8aa3b, v88
	v_mul_f32_e32 v181, 0xbfb8aa3b, v89
	v_mul_f32_e32 v182, 0xbfb8aa3b, v90
	v_mul_f32_e32 v183, 0xbfb8aa3b, v91
	v_exp_f32_e32 v176, v176
	v_exp_f32_e32 v177, v177
	v_exp_f32_e32 v178, v178
	v_exp_f32_e32 v179, v179
	v_exp_f32_e32 v180, v180
	v_exp_f32_e32 v181, v181
	v_exp_f32_e32 v182, v182
	v_exp_f32_e32 v183, v183
	v_add_f32_e32 v176, 1.0, v176
	v_add_f32_e32 v177, 1.0, v177
	v_add_f32_e32 v178, 1.0, v178
	v_add_f32_e32 v179, 1.0, v179
	v_add_f32_e32 v180, 1.0, v180
	v_add_f32_e32 v181, 1.0, v181
	v_add_f32_e32 v182, 1.0, v182
	v_add_f32_e32 v183, 1.0, v183
	v_rcp_f32_e32 v176, v176
	v_rcp_f32_e32 v177, v177
	v_rcp_f32_e32 v178, v178
	v_rcp_f32_e32 v179, v179
	v_rcp_f32_e32 v180, v180
	v_rcp_f32_e32 v181, v181
	v_rcp_f32_e32 v182, v182
	v_rcp_f32_e32 v183, v183
	v_pk_mul_f32 v[176:177], v[92:93], v[176:177]
	v_pk_mul_f32 v[178:179], v[94:95], v[178:179]
	v_pk_mul_f32 v[180:181], v[88:89], v[180:181]
	v_pk_mul_f32 v[182:183], v[90:91], v[182:183]
	v_cvt_pk_bf16_f32 v128, v176, v177
	v_cvt_pk_bf16_f32 v129, v178, v179
	v_cvt_pk_bf16_f32 v130, v180, v181
	v_cvt_pk_bf16_f32 v131, v182, v183
	global_store_dwordx4 v[134:135], v[128:131], off
	v_mul_f32_e32 v216, 0xbfb8aa3b, v84
	v_mul_f32_e32 v217, 0xbfb8aa3b, v85
	v_mul_f32_e32 v218, 0xbfb8aa3b, v86
	v_mul_f32_e32 v219, 0xbfb8aa3b, v87
	v_mul_f32_e32 v220, 0xbfb8aa3b, v80
	v_mul_f32_e32 v221, 0xbfb8aa3b, v81
	v_mul_f32_e32 v222, 0xbfb8aa3b, v82
	v_mul_f32_e32 v223, 0xbfb8aa3b, v83
	v_exp_f32_e32 v216, v216
	v_exp_f32_e32 v217, v217
	v_exp_f32_e32 v218, v218
	v_exp_f32_e32 v219, v219
	v_exp_f32_e32 v220, v220
	v_exp_f32_e32 v221, v221
	v_exp_f32_e32 v222, v222
	v_exp_f32_e32 v223, v223
	v_add_f32_e32 v216, 1.0, v216
	v_add_f32_e32 v217, 1.0, v217
	v_add_f32_e32 v218, 1.0, v218
	v_add_f32_e32 v219, 1.0, v219
	v_add_f32_e32 v220, 1.0, v220
	v_add_f32_e32 v221, 1.0, v221
	v_add_f32_e32 v222, 1.0, v222
	v_add_f32_e32 v223, 1.0, v223
	v_rcp_f32_e32 v216, v216
	v_rcp_f32_e32 v217, v217
	v_rcp_f32_e32 v218, v218
	v_rcp_f32_e32 v219, v219
	v_rcp_f32_e32 v220, v220
	v_rcp_f32_e32 v221, v221
	v_rcp_f32_e32 v222, v222
	v_rcp_f32_e32 v223, v223
	v_pk_mul_f32 v[216:217], v[84:85], v[216:217]
	v_pk_mul_f32 v[218:219], v[86:87], v[218:219]
	v_pk_mul_f32 v[220:221], v[80:81], v[220:221]
	v_pk_mul_f32 v[222:223], v[82:83], v[222:223]
	v_cvt_pk_bf16_f32 v136, v216, v217
	v_cvt_pk_bf16_f32 v137, v218, v219
	v_cvt_pk_bf16_f32 v138, v220, v221
	v_cvt_pk_bf16_f32 v139, v222, v223
	global_store_dwordx4 v[134:135], v[136:139], off offset:256
	s_mov_b64 s[8:9], 0x150000
	s_nop 0
	v_lshl_add_u64 v[174:175], v[132:133], 0, s[8:9]
	v_mul_f32_e32 v176, 0xbfb8aa3b, v76
	v_mul_f32_e32 v177, 0xbfb8aa3b, v77
	v_mul_f32_e32 v178, 0xbfb8aa3b, v78
	v_mul_f32_e32 v179, 0xbfb8aa3b, v79
	v_mul_f32_e32 v180, 0xbfb8aa3b, v72
	v_mul_f32_e32 v181, 0xbfb8aa3b, v73
	v_mul_f32_e32 v182, 0xbfb8aa3b, v74
	v_mul_f32_e32 v183, 0xbfb8aa3b, v75
	v_exp_f32_e32 v176, v176
; __device__ __forceinline__ u32x4 pack8(const float (&f)[8]) { u32x4 w; w.x = cvt_pk_bf16(f[0], f[1]); w.y = cvt_pk_bf16(f[2], f[3]); w.z = cvt_pk_bf16(f[4], f[5]); w.w = cvt_pk_bf16(f[6], f[7]); return w; }
; __device__ __forceinline__ float sigmoidf_(float x) { return __builtin_amdgcn_rcpf(1.0f + __builtin_amdgcn_exp2f(-1.4426950408889634f * x)); }
; __device__ __forceinline__ float siluf_(float x) { return x * sigmoidf_(x); }
;     __device__ __forceinline__ void operator()(const Acc& acc, const Unit& u, int wr, int wc, int fr, int fq) const {
;     ...
;                     } else if (mode == 2) {
; #pragma unroll
;                         for (int e = 0; e < 8; ++e) v[e] = siluf_(v[e]);
;                     } else if (mode == 4) {
; #pragma unroll
;                         for (int e = 0; e < 8; ++e) v[e] = sigmoidf_(v[e] + bg[e]);
;                     }
;                     const u32x4 w = pack8(v);
	v_exp_f32_e32 v177, v177
	v_exp_f32_e32 v178, v178
	v_exp_f32_e32 v179, v179
	v_exp_f32_e32 v180, v180
	v_exp_f32_e32 v181, v181
	v_exp_f32_e32 v182, v182
	v_exp_f32_e32 v183, v183
	v_add_f32_e32 v176, 1.0, v176
	v_add_f32_e32 v177, 1.0, v177
	v_add_f32_e32 v178, 1.0, v178
	v_add_f32_e32 v179, 1.0, v179
	v_add_f32_e32 v180, 1.0, v180
	v_add_f32_e32 v181, 1.0, v181
	v_add_f32_e32 v182, 1.0, v182
	v_add_f32_e32 v183, 1.0, v183
	v_rcp_f32_e32 v176, v176
	v_rcp_f32_e32 v177, v177
	v_rcp_f32_e32 v178, v178
	v_rcp_f32_e32 v179, v179
	v_rcp_f32_e32 v180, v180
	v_rcp_f32_e32 v181, v181
	v_rcp_f32_e32 v182, v182
	v_rcp_f32_e32 v183, v183
	v_pk_mul_f32 v[176:177], v[76:77], v[176:177]
	v_pk_mul_f32 v[178:179], v[78:79], v[178:179]
	v_pk_mul_f32 v[180:181], v[72:73], v[180:181]
	v_pk_mul_f32 v[182:183], v[74:75], v[182:183]
	v_cvt_pk_bf16_f32 v140, v176, v177
	v_cvt_pk_bf16_f32 v141, v178, v179
	v_cvt_pk_bf16_f32 v142, v180, v181
	v_cvt_pk_bf16_f32 v143, v182, v183
	global_store_dwordx4 v[174:175], v[140:143], off
	v_mul_f32_e32 v216, 0xbfb8aa3b, v68
	v_mul_f32_e32 v217, 0xbfb8aa3b, v69
	v_mul_f32_e32 v218, 0xbfb8aa3b, v70
	v_mul_f32_e32 v219, 0xbfb8aa3b, v71
	v_mul_f32_e32 v220, 0xbfb8aa3b, v64
	v_mul_f32_e32 v221, 0xbfb8aa3b, v65
	v_mul_f32_e32 v222, 0xbfb8aa3b, v66
	v_mul_f32_e32 v223, 0xbfb8aa3b, v67
	v_exp_f32_e32 v216, v216
	v_exp_f32_e32 v217, v217
	v_exp_f32_e32 v218, v218
	v_exp_f32_e32 v219, v219
	v_exp_f32_e32 v220, v220
	v_exp_f32_e32 v221, v221
	v_exp_f32_e32 v222, v222
	v_exp_f32_e32 v223, v223
	v_add_f32_e32 v216, 1.0, v216
	v_add_f32_e32 v217, 1.0, v217
	v_add_f32_e32 v218, 1.0, v218
	v_add_f32_e32 v219, 1.0, v219
	v_add_f32_e32 v220, 1.0, v220
	v_add_f32_e32 v221, 1.0, v221
	v_add_f32_e32 v222, 1.0, v222
	v_add_f32_e32 v223, 1.0, v223
	v_rcp_f32_e32 v216, v216
	v_rcp_f32_e32 v217, v217
	v_rcp_f32_e32 v218, v218
	v_rcp_f32_e32 v219, v219
	v_rcp_f32_e32 v220, v220
	v_rcp_f32_e32 v221, v221
	v_rcp_f32_e32 v222, v222
	v_rcp_f32_e32 v223, v223
	v_pk_mul_f32 v[216:217], v[68:69], v[216:217]
	v_pk_mul_f32 v[218:219], v[70:71], v[218:219]
	v_pk_mul_f32 v[220:221], v[64:65], v[220:221]
	v_pk_mul_f32 v[222:223], v[66:67], v[222:223]
	v_cvt_pk_bf16_f32 v170, v216, v217
	v_cvt_pk_bf16_f32 v171, v218, v219
	v_cvt_pk_bf16_f32 v172, v220, v221
	v_cvt_pk_bf16_f32 v173, v222, v223
	global_store_dwordx4 v[174:175], v[170:173], off offset:256
	s_mov_b64 s[8:9], 0x380000
	s_nop 0
	v_lshl_add_u64 v[134:135], v[132:133], 0, s[8:9]
	v_mul_f32_e32 v176, 0xbfb8aa3b, v60
	v_mul_f32_e32 v177, 0xbfb8aa3b, v61
	v_mul_f32_e32 v178, 0xbfb8aa3b, v62
	v_mul_f32_e32 v179, 0xbfb8aa3b, v63
	v_mul_f32_e32 v180, 0xbfb8aa3b, v56
	v_mul_f32_e32 v181, 0xbfb8aa3b, v57
	v_mul_f32_e32 v182, 0xbfb8aa3b, v58
	v_mul_f32_e32 v183, 0xbfb8aa3b, v59
	v_exp_f32_e32 v176, v176
	v_exp_f32_e32 v177, v177
	v_exp_f32_e32 v178, v178
	v_exp_f32_e32 v179, v179
	v_exp_f32_e32 v180, v180
	v_exp_f32_e32 v181, v181
	v_exp_f32_e32 v182, v182
	v_exp_f32_e32 v183, v183
	v_add_f32_e32 v176, 1.0, v176
	v_add_f32_e32 v177, 1.0, v177
	v_add_f32_e32 v178, 1.0, v178
	v_add_f32_e32 v179, 1.0, v179
	v_add_f32_e32 v180, 1.0, v180
	v_add_f32_e32 v181, 1.0, v181
	v_add_f32_e32 v182, 1.0, v182
	v_add_f32_e32 v183, 1.0, v183
	v_rcp_f32_e32 v176, v176
	v_rcp_f32_e32 v177, v177
	v_rcp_f32_e32 v178, v178
	v_rcp_f32_e32 v179, v179
	v_rcp_f32_e32 v180, v180
	v_rcp_f32_e32 v181, v181
	v_rcp_f32_e32 v182, v182
	v_rcp_f32_e32 v183, v183
	v_pk_mul_f32 v[176:177], v[60:61], v[176:177]
	v_pk_mul_f32 v[178:179], v[62:63], v[178:179]
	v_pk_mul_f32 v[180:181], v[56:57], v[180:181]
	v_pk_mul_f32 v[182:183], v[58:59], v[182:183]
	v_cvt_pk_bf16_f32 v128, v176, v177
	v_cvt_pk_bf16_f32 v129, v178, v179
	v_cvt_pk_bf16_f32 v130, v180, v181
	v_cvt_pk_bf16_f32 v131, v182, v183
	global_store_dwordx4 v[134:135], v[128:131], off
	v_mul_f32_e32 v216, 0xbfb8aa3b, v52
	v_mul_f32_e32 v217, 0xbfb8aa3b, v53
	v_mul_f32_e32 v218, 0xbfb8aa3b, v54
	v_mul_f32_e32 v219, 0xbfb8aa3b, v55
	v_mul_f32_e32 v220, 0xbfb8aa3b, v48
	v_mul_f32_e32 v221, 0xbfb8aa3b, v49
	v_mul_f32_e32 v222, 0xbfb8aa3b, v50
	v_mul_f32_e32 v223, 0xbfb8aa3b, v51
	v_exp_f32_e32 v216, v216
	v_exp_f32_e32 v217, v217
	v_exp_f32_e32 v218, v218
	v_exp_f32_e32 v219, v219
	v_exp_f32_e32 v220, v220
	v_exp_f32_e32 v221, v221
	v_exp_f32_e32 v222, v222
	v_exp_f32_e32 v223, v223
	v_add_f32_e32 v216, 1.0, v216
	v_add_f32_e32 v217, 1.0, v217
	v_add_f32_e32 v218, 1.0, v218
	v_add_f32_e32 v219, 1.0, v219
	v_add_f32_e32 v220, 1.0, v220
	v_add_f32_e32 v221, 1.0, v221
	v_add_f32_e32 v222, 1.0, v222
	v_add_f32_e32 v223, 1.0, v223
	v_rcp_f32_e32 v216, v216
	v_rcp_f32_e32 v217, v217
	v_rcp_f32_e32 v218, v218
	v_rcp_f32_e32 v219, v219
	v_rcp_f32_e32 v220, v220
	v_rcp_f32_e32 v221, v221
	v_rcp_f32_e32 v222, v222
	v_rcp_f32_e32 v223, v223
	v_pk_mul_f32 v[216:217], v[52:53], v[216:217]
	v_pk_mul_f32 v[218:219], v[54:55], v[218:219]
	v_pk_mul_f32 v[220:221], v[48:49], v[220:221]
	v_pk_mul_f32 v[222:223], v[50:51], v[222:223]
	v_cvt_pk_bf16_f32 v136, v216, v217
	v_cvt_pk_bf16_f32 v137, v218, v219
	v_cvt_pk_bf16_f32 v138, v220, v221
	v_cvt_pk_bf16_f32 v139, v222, v223
	global_store_dwordx4 v[134:135], v[136:139], off offset:256
	s_mov_b64 s[8:9], 0x3f0000
	s_nop 0
	v_lshl_add_u64 v[174:175], v[132:133], 0, s[8:9]
	v_mul_f32_e32 v176, 0xbfb8aa3b, v44
	v_mul_f32_e32 v177, 0xbfb8aa3b, v45
	v_mul_f32_e32 v178, 0xbfb8aa3b, v46
	v_mul_f32_e32 v179, 0xbfb8aa3b, v47
	v_mul_f32_e32 v180, 0xbfb8aa3b, v40
	v_mul_f32_e32 v181, 0xbfb8aa3b, v41
	v_mul_f32_e32 v182, 0xbfb8aa3b, v42
	v_mul_f32_e32 v183, 0xbfb8aa3b, v43
	v_exp_f32_e32 v176, v176
	v_exp_f32_e32 v177, v177
	v_exp_f32_e32 v178, v178
	v_exp_f32_e32 v179, v179
; __device__ __forceinline__ u32x4 pack8(const float (&f)[8]) { u32x4 w; w.x = cvt_pk_bf16(f[0], f[1]); w.y = cvt_pk_bf16(f[2], f[3]); w.z = cvt_pk_bf16(f[4], f[5]); w.w = cvt_pk_bf16(f[6], f[7]); return w; }
; __device__ __forceinline__ float sigmoidf_(float x) { return __builtin_amdgcn_rcpf(1.0f + __builtin_amdgcn_exp2f(-1.4426950408889634f * x)); }
; __device__ __forceinline__ float siluf_(float x) { return x * sigmoidf_(x); }
;     __device__ __forceinline__ void operator()(const Acc& acc, const Unit& u, int wr, int wc, int fr, int fq) const {
;     ...
;                     } else if (mode == 2) {
; #pragma unroll
;                         for (int e = 0; e < 8; ++e) v[e] = siluf_(v[e]);
;                     } else if (mode == 4) {
; #pragma unroll
;                         for (int e = 0; e < 8; ++e) v[e] = sigmoidf_(v[e] + bg[e]);
;                     }
;                     const u32x4 w = pack8(v);
	v_exp_f32_e32 v180, v180
	v_exp_f32_e32 v181, v181
	v_exp_f32_e32 v182, v182
	v_exp_f32_e32 v183, v183
	v_add_f32_e32 v176, 1.0, v176
	v_add_f32_e32 v177, 1.0, v177
	v_add_f32_e32 v178, 1.0, v178
	v_add_f32_e32 v179, 1.0, v179
	v_add_f32_e32 v180, 1.0, v180
	v_add_f32_e32 v181, 1.0, v181
	v_add_f32_e32 v182, 1.0, v182
	v_add_f32_e32 v183, 1.0, v183
	v_rcp_f32_e32 v176, v176
	v_rcp_f32_e32 v177, v177
	v_rcp_f32_e32 v178, v178
	v_rcp_f32_e32 v179, v179
	v_rcp_f32_e32 v180, v180
	v_rcp_f32_e32 v181, v181
	v_rcp_f32_e32 v182, v182
	v_rcp_f32_e32 v183, v183
	v_pk_mul_f32 v[176:177], v[44:45], v[176:177]
	v_pk_mul_f32 v[178:179], v[46:47], v[178:179]
	v_pk_mul_f32 v[180:181], v[40:41], v[180:181]
	v_pk_mul_f32 v[182:183], v[42:43], v[182:183]
	v_cvt_pk_bf16_f32 v140, v176, v177
	v_cvt_pk_bf16_f32 v141, v178, v179
	v_cvt_pk_bf16_f32 v142, v180, v181
	v_cvt_pk_bf16_f32 v143, v182, v183
	global_store_dwordx4 v[174:175], v[140:143], off
	v_mul_f32_e32 v216, 0xbfb8aa3b, v36
	v_mul_f32_e32 v217, 0xbfb8aa3b, v37
	v_mul_f32_e32 v218, 0xbfb8aa3b, v38
	v_mul_f32_e32 v219, 0xbfb8aa3b, v39
	v_mul_f32_e32 v220, 0xbfb8aa3b, v32
	v_mul_f32_e32 v221, 0xbfb8aa3b, v33
	v_mul_f32_e32 v222, 0xbfb8aa3b, v34
	v_mul_f32_e32 v223, 0xbfb8aa3b, v35
	v_exp_f32_e32 v216, v216
	v_exp_f32_e32 v217, v217
	v_exp_f32_e32 v218, v218
	v_exp_f32_e32 v219, v219
	v_exp_f32_e32 v220, v220
	v_exp_f32_e32 v221, v221
	v_exp_f32_e32 v222, v222
	v_exp_f32_e32 v223, v223
	v_add_f32_e32 v216, 1.0, v216
	v_add_f32_e32 v217, 1.0, v217
	v_add_f32_e32 v218, 1.0, v218
	v_add_f32_e32 v219, 1.0, v219
	v_add_f32_e32 v220, 1.0, v220
	v_add_f32_e32 v221, 1.0, v221
	v_add_f32_e32 v222, 1.0, v222
	v_add_f32_e32 v223, 1.0, v223
	v_rcp_f32_e32 v216, v216
	v_rcp_f32_e32 v217, v217
	v_rcp_f32_e32 v218, v218
	v_rcp_f32_e32 v219, v219
	v_rcp_f32_e32 v220, v220
	v_rcp_f32_e32 v221, v221
	v_rcp_f32_e32 v222, v222
	v_rcp_f32_e32 v223, v223
	v_pk_mul_f32 v[216:217], v[36:37], v[216:217]
	v_pk_mul_f32 v[218:219], v[38:39], v[218:219]
	v_pk_mul_f32 v[220:221], v[32:33], v[220:221]
	v_pk_mul_f32 v[222:223], v[34:35], v[222:223]
	v_cvt_pk_bf16_f32 v170, v216, v217
	v_cvt_pk_bf16_f32 v171, v218, v219
	v_cvt_pk_bf16_f32 v172, v220, v221
	v_cvt_pk_bf16_f32 v173, v222, v223
	global_store_dwordx4 v[174:175], v[170:173], off offset:256
	s_mov_b64 s[8:9], 0x460000
	s_nop 0
	v_lshl_add_u64 v[134:135], v[132:133], 0, s[8:9]
	v_mul_f32_e32 v176, 0xbfb8aa3b, v28
	v_mul_f32_e32 v177, 0xbfb8aa3b, v29
	v_mul_f32_e32 v178, 0xbfb8aa3b, v30
	v_mul_f32_e32 v179, 0xbfb8aa3b, v31
	v_mul_f32_e32 v180, 0xbfb8aa3b, v24
	v_mul_f32_e32 v181, 0xbfb8aa3b, v25
	v_mul_f32_e32 v182, 0xbfb8aa3b, v26
	v_mul_f32_e32 v183, 0xbfb8aa3b, v27
	v_exp_f32_e32 v176, v176
	v_exp_f32_e32 v177, v177
	v_exp_f32_e32 v178, v178
	v_exp_f32_e32 v179, v179
	v_exp_f32_e32 v180, v180
	v_exp_f32_e32 v181, v181
	v_exp_f32_e32 v182, v182
	v_exp_f32_e32 v183, v183
	v_add_f32_e32 v176, 1.0, v176
	v_add_f32_e32 v177, 1.0, v177
	v_add_f32_e32 v178, 1.0, v178
	v_add_f32_e32 v179, 1.0, v179
	v_add_f32_e32 v180, 1.0, v180
	v_add_f32_e32 v181, 1.0, v181
	v_add_f32_e32 v182, 1.0, v182
	v_add_f32_e32 v183, 1.0, v183
	v_rcp_f32_e32 v176, v176
	v_rcp_f32_e32 v177, v177
	v_rcp_f32_e32 v178, v178
	v_rcp_f32_e32 v179, v179
	v_rcp_f32_e32 v180, v180
	v_rcp_f32_e32 v181, v181
	v_rcp_f32_e32 v182, v182
	v_rcp_f32_e32 v183, v183
	v_pk_mul_f32 v[176:177], v[28:29], v[176:177]
	v_pk_mul_f32 v[178:179], v[30:31], v[178:179]
	v_pk_mul_f32 v[180:181], v[24:25], v[180:181]
	v_pk_mul_f32 v[182:183], v[26:27], v[182:183]
	v_cvt_pk_bf16_f32 v128, v176, v177
	v_cvt_pk_bf16_f32 v129, v178, v179
	v_cvt_pk_bf16_f32 v130, v180, v181
	v_cvt_pk_bf16_f32 v131, v182, v183
	global_store_dwordx4 v[134:135], v[128:131], off
	v_mul_f32_e32 v216, 0xbfb8aa3b, v20
	v_mul_f32_e32 v217, 0xbfb8aa3b, v21
	v_mul_f32_e32 v218, 0xbfb8aa3b, v22
	v_mul_f32_e32 v219, 0xbfb8aa3b, v23
	v_mul_f32_e32 v220, 0xbfb8aa3b, v16
	v_mul_f32_e32 v221, 0xbfb8aa3b, v17
	v_mul_f32_e32 v222, 0xbfb8aa3b, v18
	v_mul_f32_e32 v223, 0xbfb8aa3b, v19
	v_exp_f32_e32 v216, v216
	v_exp_f32_e32 v217, v217
	v_exp_f32_e32 v218, v218
	v_exp_f32_e32 v219, v219
	v_exp_f32_e32 v220, v220
; __device__ __forceinline__ float sigmoidf_(float x) { return __builtin_amdgcn_rcpf(1.0f + __builtin_amdgcn_exp2f(-1.4426950408889634f * x)); }
; __device__ __forceinline__ float siluf_(float x) { return x * sigmoidf_(x); }
;     __device__ __forceinline__ void operator()(const Acc& acc, const Unit& u, int wr, int wc, int fr, int fq) const {
;     ...
;         int mode = 0;
;         if (pn < 2) mode = 1; else if (pn == 6 || pn == 7 || pn == 10 || pn == 11 || pn == 18 || pn == 19 || pn == 22 || pn == 23) mode = 2;
;         else if (pn == 20 || pn == 21) mode = 3; else if (pn >= 24) mode = 4;
; #pragma unroll
;         for (int bj = 0; bj < 2; ++bj) {
;             const int col = col0 + bj * 128;
;             float bg[8];
; #pragma unroll
;             for (int e = 0; e < 8; ++e) bg[e] = 0.f;
;             if (mode == 4) { const f32x4 b0 = *(const f32x4*)(bgate + col - 6144), b1 = *(const f32x4*)(bgate + col - 6144 + 4);
; #pragma unroll
;                 for (int e = 0; e < 4; ++e) { bg[e] = b0[e]; bg[4 + e] = b1[e]; } }
; #pragma unroll
;             for (int ai = 0; ai < 2; ++ai)
; #pragma unroll
;                 for (int m = 0; m < 4; ++m) {
;                     const int row = row0 + ai * 128 + m * 16;
;                     float v[8];
; #pragma unroll
;                     for (int e = 0; e < 4; ++e) { v[e] = acc[ai][bj][m][0][e]; v[4 + e] = acc[ai][bj][m][1][e]; }
;                     if (mode == 1) {
; #pragma unroll
;                         for (int e = 0; e < 8; ++e) v[e] *= 0.125f;
;                     } else if (mode == 2) {
; #pragma unroll
;                         for (int e = 0; e < 8; ++e) v[e] = siluf_(v[e]);
;                     } else if (mode == 4) {
; #pragma unroll
;                         for (int e = 0; e < 8; ++e) v[e] = sigmoidf_(v[e] + bg[e]);
;                     }
;                     const u32x4 w = pack8(v);
;                     if (mode == 3) { const int cc = col - 5120, g = cc >> 4, h0 = cc & 15, n = row >> 4, j = row & 15;
;                         *(u32x4*)(X + ((size_t)(g * XROWS + n) * 512 + j * 16 + h0)) = w; }
;                     else *(u32x4*)(proj + (size_t)row * NIN + col) = w;
;                 }
;         }
	v_exp_f32_e32 v221, v221
	v_exp_f32_e32 v222, v222
	v_exp_f32_e32 v223, v223
	v_add_f32_e32 v216, 1.0, v216
	v_add_f32_e32 v217, 1.0, v217
	v_add_f32_e32 v218, 1.0, v218
	v_add_f32_e32 v219, 1.0, v219
	v_add_f32_e32 v220, 1.0, v220
	v_add_f32_e32 v221, 1.0, v221
	v_add_f32_e32 v222, 1.0, v222
	v_add_f32_e32 v223, 1.0, v223
	v_rcp_f32_e32 v216, v216
	v_rcp_f32_e32 v217, v217
	v_rcp_f32_e32 v218, v218
	v_rcp_f32_e32 v219, v219
	v_rcp_f32_e32 v220, v220
	v_rcp_f32_e32 v221, v221
	v_rcp_f32_e32 v222, v222
	v_rcp_f32_e32 v223, v223
	v_pk_mul_f32 v[216:217], v[20:21], v[216:217]
	v_pk_mul_f32 v[218:219], v[22:23], v[218:219]
	v_pk_mul_f32 v[220:221], v[16:17], v[220:221]
	v_pk_mul_f32 v[222:223], v[18:19], v[222:223]
	v_cvt_pk_bf16_f32 v136, v216, v217
	v_cvt_pk_bf16_f32 v137, v218, v219
	v_cvt_pk_bf16_f32 v138, v220, v221
	v_cvt_pk_bf16_f32 v139, v222, v223
	global_store_dwordx4 v[134:135], v[136:139], off offset:256
	s_mov_b64 s[8:9], 0x4d0000
	s_nop 0
	v_lshl_add_u64 v[174:175], v[132:133], 0, s[8:9]
	v_mul_f32_e32 v176, 0xbfb8aa3b, v12
	v_mul_f32_e32 v177, 0xbfb8aa3b, v13
	v_mul_f32_e32 v178, 0xbfb8aa3b, v14
	v_mul_f32_e32 v179, 0xbfb8aa3b, v15
	v_mul_f32_e32 v180, 0xbfb8aa3b, v8
	v_mul_f32_e32 v181, 0xbfb8aa3b, v9
	v_mul_f32_e32 v182, 0xbfb8aa3b, v10
	v_mul_f32_e32 v183, 0xbfb8aa3b, v11
	v_exp_f32_e32 v176, v176
	v_exp_f32_e32 v177, v177
	v_exp_f32_e32 v178, v178
	v_exp_f32_e32 v179, v179
	v_exp_f32_e32 v180, v180
	v_exp_f32_e32 v181, v181
	v_exp_f32_e32 v182, v182
	v_exp_f32_e32 v183, v183
	v_add_f32_e32 v176, 1.0, v176
	v_add_f32_e32 v177, 1.0, v177
	v_add_f32_e32 v178, 1.0, v178
	v_add_f32_e32 v179, 1.0, v179
	v_add_f32_e32 v180, 1.0, v180
	v_add_f32_e32 v181, 1.0, v181
	v_add_f32_e32 v182, 1.0, v182
	v_add_f32_e32 v183, 1.0, v183
	v_rcp_f32_e32 v176, v176
	v_rcp_f32_e32 v177, v177
	v_rcp_f32_e32 v178, v178
	v_rcp_f32_e32 v179, v179
	v_rcp_f32_e32 v180, v180
	v_rcp_f32_e32 v181, v181
	v_rcp_f32_e32 v182, v182
	v_rcp_f32_e32 v183, v183
	v_pk_mul_f32 v[176:177], v[12:13], v[176:177]
	v_pk_mul_f32 v[178:179], v[14:15], v[178:179]
	v_pk_mul_f32 v[180:181], v[8:9], v[180:181]
	v_pk_mul_f32 v[182:183], v[10:11], v[182:183]
	v_cvt_pk_bf16_f32 v140, v176, v177
	v_cvt_pk_bf16_f32 v141, v178, v179
	v_cvt_pk_bf16_f32 v142, v180, v181
	v_cvt_pk_bf16_f32 v143, v182, v183
	global_store_dwordx4 v[174:175], v[140:143], off
	v_mul_f32_e32 v216, 0xbfb8aa3b, v4
	v_mul_f32_e32 v217, 0xbfb8aa3b, v5
	v_mul_f32_e32 v218, 0xbfb8aa3b, v6
	v_mul_f32_e32 v219, 0xbfb8aa3b, v7
	v_mul_f32_e32 v220, 0xbfb8aa3b, v0
	v_mul_f32_e32 v221, 0xbfb8aa3b, v1
	v_mul_f32_e32 v222, 0xbfb8aa3b, v2
	v_mul_f32_e32 v223, 0xbfb8aa3b, v3
	v_exp_f32_e32 v216, v216
	v_exp_f32_e32 v217, v217
	v_exp_f32_e32 v218, v218
	v_exp_f32_e32 v219, v219
	v_exp_f32_e32 v220, v220
	v_exp_f32_e32 v221, v221
	v_exp_f32_e32 v222, v222
	v_exp_f32_e32 v223, v223
	v_add_f32_e32 v216, 1.0, v216
	v_add_f32_e32 v217, 1.0, v217
	v_add_f32_e32 v218, 1.0, v218
	v_add_f32_e32 v219, 1.0, v219
	v_add_f32_e32 v220, 1.0, v220
	v_add_f32_e32 v221, 1.0, v221
	v_add_f32_e32 v222, 1.0, v222
	v_add_f32_e32 v223, 1.0, v223
	v_rcp_f32_e32 v216, v216
	v_rcp_f32_e32 v217, v217
	v_rcp_f32_e32 v218, v218
	v_rcp_f32_e32 v219, v219
	v_rcp_f32_e32 v220, v220
	v_rcp_f32_e32 v221, v221
	v_rcp_f32_e32 v222, v222
	v_rcp_f32_e32 v223, v223
	v_pk_mul_f32 v[216:217], v[4:5], v[216:217]
	v_pk_mul_f32 v[218:219], v[6:7], v[218:219]
	v_pk_mul_f32 v[220:221], v[0:1], v[220:221]
	v_pk_mul_f32 v[222:223], v[2:3], v[222:223]
	v_cvt_pk_bf16_f32 v170, v216, v217
	v_cvt_pk_bf16_f32 v171, v218, v219
	v_cvt_pk_bf16_f32 v172, v220, v221
	v_cvt_pk_bf16_f32 v173, v222, v223
	global_store_dwordx4 v[174:175], v[170:173], off offset:256
	s_branch .LBB0_723
.Lepi_orig:
	s_cmp_gt_i32 s4, 1
	s_mov_b64 s[6:7], 0
	s_cselect_b64 s[10:11], -1, 0
	s_cmp_lt_i32 s4, 2
	s_mov_b64 s[8:9], 0
	s_cbranch_scc1 .LBB0_560
	s_and_b32 s8, s4, 0x7ffffffe
	s_add_i32 s6, s8, -6
	v_alignbit_b32 v128, s6, s6, 2
	v_cmp_gt_u32_e32 vcc, 5, v128
	v_readfirstlane_b32 s9, v128
	v_cmp_lt_u32_e64 s[6:7], 4, v128
	s_cbranch_vccz .LBB0_557
	s_lshr_b32 s6, 27, s9
	s_bitcmp1_b32 s6, 0
	s_cselect_b64 s[6:7], -1, 0
	s_xor_b64 s[6:7], s[6:7], -1
